# epilogue pass-1: prefetch the second column half's T/x cache lines with the first batch (PH6, PH9, PH12)
# baseline (speedup 1.0000x reference)
.LBB0_2298:
	s_mov_b32 s0, 0
	s_mov_b32 s1, 0
	s_mov_b32 s4, 0
	s_mov_b32 s5, 0
	s_mov_b32 s97, s33
	s_mov_b32 s85, s14
	v_mbcnt_lo_u32_b32 v2, -1, 0
	v_mbcnt_hi_u32_b32 v2, -1, v2
	s_mul_i32 s73, s94, 0xc0
	s_lshl_b32 s15, s85, 5
	s_lshl_b32 s0, s72, 8
	s_add_i32 s95, s15, s0
	s_add_i32 s0, s73, 0xfffff000
	s_lshr_b32 s0, s0, 12
	s_add_i32 s0, s0, 1
	s_cmp_gt_i32 s94, 21
	s_cselect_b32 s0, s0, 0
	s_add_i32 s1, s73, 0xfffff0bf
	s_lshr_b32 s1, s1, 12
	s_add_i32 s1, s1, 1
	s_cmp_gt_i32 s94, 20
	s_cselect_b32 s1, s1, 0
	s_lshl_b32 s4, s1, 12
	s_cmp_lg_u32 s1, s0
	s_mul_i32 s16, s0, 0x1800
	s_mul_i32 s96, s97, 48
	v_ashrrev_i32_e32 v0, 1, v2
	s_cselect_b32 s63, s4, 0x7fffffff
	s_lshl_b64 s[76:77], s[16:17], 2
	v_and_or_b32 v144, v2, 15, s96
	v_and_b32_e32 v0, -8, v0
	s_mul_i32 s4, s1, 0x1800
	s_mov_b32 s5, s17
	s_add_u32 s0, s83, s76
	v_readlane_b32 s36, v255, 40
	v_add_u32_e32 v170, s73, v144
	v_add_u32_e32 v168, s95, v0
	s_addc_u32 s1, s84, s77
	s_lshl_b64 s[74:75], s[4:5], 2
	s_movk_i32 s4, 0x1000
	v_readlane_b32 s37, v255, 41
	v_mov_b32_e32 v128, 2.0
	v_mov_b32_e32 v126, 0x3a800000
	v_mov_b32_e32 v0, v168
	v_cmp_gt_i32_e32 vcc, s4, v170
	v_readlane_b32 s38, v255, 42
	v_readlane_b32 s39, v255, 43
	s_mov_b64 s[4:5], s[36:37]
	s_mov_b64 s[6:7], s[38:39]
	v_ashrrev_i32_e32 v1, 31, v0
	v_lshlrev_b64 v[8:9], 2, v[0:1]
	v_add_u32_e32 v0, 0xfffff000, v170
	v_ashrrev_i32_e32 v171, 31, v170
	v_mov_b32_e32 v117, s7
	v_mov_b32_e32 v127, s5
	v_mov_b32_e32 v129, s6
	v_mov_b32_e32 v140, s4
	v_add_u32_e32 v178, 16, v170
	s_movk_i32 s4, 0xff0
	v_cndmask_b32_e32 v1, 0, v171, vcc
	v_cndmask_b32_e32 v0, v0, v170, vcc
	v_cndmask_b32_e32 v11, v117, v127, vcc
	v_cndmask_b32_e32 v10, v129, v140, vcc
	v_ashrrev_i32_e32 v179, 31, v178
	v_add_u32_e32 v130, 0xfffff010, v170
	v_cmp_gt_i32_e32 vcc, s4, v170
	v_add_u32_e32 v176, 32, v170
	s_movk_i32 s4, 0xfe0
	v_cndmask_b32_e32 v131, 0, v179, vcc
	v_cndmask_b32_e32 v130, v130, v178, vcc
	v_cndmask_b32_e32 v133, v117, v127, vcc
	v_cndmask_b32_e32 v132, v129, v140, vcc
	v_lshlrev_b64 v[130:131], 12, v[130:131]
	v_lshl_add_u64 v[130:131], v[132:133], 0, v[130:131]
	v_ashrrev_i32_e32 v177, 31, v176
	v_add_u32_e32 v132, 0xfffff020, v170
	v_cmp_gt_i32_e32 vcc, s4, v170
	v_add_u32_e32 v174, 0x60, v170
	s_movk_i32 s4, 0xfa0
	v_cndmask_b32_e32 v133, 0, v177, vcc
	v_cndmask_b32_e32 v132, v132, v176, vcc
	v_cndmask_b32_e32 v135, v117, v127, vcc
	v_cndmask_b32_e32 v134, v129, v140, vcc
	v_lshlrev_b64 v[132:133], 12, v[132:133]
	v_lshl_add_u64 v[132:133], v[134:135], 0, v[132:133]
	v_ashrrev_i32_e32 v175, 31, v174
	v_add_u32_e32 v134, 0xfffff060, v170
	v_cmp_gt_i32_e32 vcc, s4, v170
	v_add_u32_e32 v172, 0x70, v170
	s_movk_i32 s4, 0xf90
	v_cndmask_b32_e32 v135, 0, v175, vcc
	v_cndmask_b32_e32 v134, v134, v174, vcc
	v_cndmask_b32_e32 v137, v117, v127, vcc
	v_cndmask_b32_e32 v136, v129, v140, vcc
	v_lshlrev_b64 v[134:135], 12, v[134:135]
	v_lshl_add_u64 v[134:135], v[136:137], 0, v[134:135]
	v_ashrrev_i32_e32 v173, 31, v172
	v_add_u32_e32 v136, 0xfffff070, v170
	v_cmp_gt_i32_e32 vcc, s4, v170
	v_add_u32_e32 v166, 0x80, v170
	s_movk_i32 s4, 0xf80
	v_cndmask_b32_e32 v137, 0, v173, vcc
	v_cndmask_b32_e32 v136, v136, v172, vcc
	v_cndmask_b32_e32 v139, v117, v127, vcc
	v_cndmask_b32_e32 v138, v129, v140, vcc
	v_lshlrev_b64 v[136:137], 12, v[136:137]
	v_lshl_add_u64 v[136:137], v[138:139], 0, v[136:137]
	v_ashrrev_i32_e32 v167, 31, v166
	v_add_u32_e32 v138, 0xfffff080, v170
	v_cmp_gt_i32_e32 vcc, s4, v170
	v_lshlrev_b64 v[0:1], 12, v[0:1]
	s_add_u32 s78, s83, s74
	v_cndmask_b32_e32 v139, 0, v167, vcc
	v_cndmask_b32_e32 v138, v138, v166, vcc
	v_cndmask_b32_e32 v141, v117, v127, vcc
	v_cndmask_b32_e32 v140, v129, v140, vcc
	v_lshlrev_b64 v[138:139], 12, v[138:139]
	v_lshl_add_u64 v[0:1], v[10:11], 0, v[0:1]
	v_lshl_add_u64 v[138:139], v[140:141], 0, v[138:139]
	s_addc_u32 s79, s84, s75
	v_lshl_add_u64 v[10:11], v[0:1], 0, v[8:9]
	v_lshl_add_u64 v[160:161], v[132:133], 0, v[8:9]
	v_lshl_add_u64 v[156:157], v[134:135], 0, v[8:9]
	v_lshl_add_u64 v[152:153], v[136:137], 0, v[8:9]
	v_lshl_add_u64 v[148:149], v[138:139], 0, v[8:9]
	v_lshl_add_u64 v[4:5], s[0:1], 0, v[8:9]
	v_lshl_add_u64 v[6:7], s[78:79], 0, v[8:9]
	v_lshl_add_u64 v[146:147], v[130:131], 0, v[8:9]
	global_load_dword v184, v[10:11], off offset:512
	global_load_dword v184, v[148:149], off offset:512
	global_load_dword v184, v[152:153], off offset:512
	global_load_dword v184, v[156:157], off offset:512
	global_load_dword v184, v[160:161], off offset:512
	global_load_dword v184, v[146:147], off offset:512
	global_load_dwordx4 v[140:143], v[10:11], off
	s_nop 0
	global_load_dwordx4 v[148:151], v[148:149], off
	s_nop 0
	global_load_dwordx4 v[152:155], v[152:153], off
	s_nop 0
	global_load_dwordx4 v[156:159], v[156:157], off
	s_nop 0
	global_load_dwordx4 v[160:163], v[160:161], off
	s_nop 0
	global_load_dwordx4 v[180:183], v[146:147], off
	global_load_dwordx4 v[184:187], v[4:5], off
	global_load_dwordx4 v[188:191], v[6:7], off
	v_readlane_b32 s40, v255, 44
	v_readlane_b32 s41, v255, 45
	v_readlane_b32 s42, v255, 46
	v_readlane_b32 s43, v255, 47
	v_readlane_b32 s44, v255, 48
	v_readlane_b32 s45, v255, 49
	v_readlane_b32 s46, v255, 50
	v_readlane_b32 s47, v255, 51
	v_readlane_b32 s48, v255, 52
	v_readlane_b32 s49, v255, 53
	v_readlane_b32 s50, v255, 54
	v_readlane_b32 s51, v255, 55
	v_readlane_b32 s36, v255, 3
	v_readlane_b32 s37, v255, 4
	v_readlane_b32 s38, v255, 5
	v_readlane_b32 s39, v255, 6
	v_readlane_b32 s40, v255, 7
	v_readlane_b32 s41, v255, 8
	v_readlane_b32 s42, v255, 9
	v_readlane_b32 s43, v255, 10
	v_readlane_b32 s44, v255, 11
	v_readlane_b32 s45, v255, 12
	v_readlane_b32 s46, v255, 13
	v_readlane_b32 s47, v255, 14
	v_readlane_b32 s48, v255, 15
	v_readlane_b32 s49, v255, 16
	v_readlane_b32 s50, v255, 17
	v_readlane_b32 s51, v255, 18
	s_mov_b64 s[30:31], s[50:51]
	v_readlane_b32 s36, v255, 19
	v_readlane_b32 s37, v255, 20
	v_lshl_add_u64 v[4:5], s[30:31], 0, v[8:9]
	global_load_dwordx4 v[4:7], v[4:5], off
	v_lshl_add_u64 v[8:9], s[36:37], 0, v[8:9]
	global_load_dwordx4 v[8:11], v[8:9], off
	s_waitcnt vmcnt(0)
	v_cmp_gt_i32_e64 s[12:13], s63, v170
	v_pk_mul_f32 v[140:141], v[140:141], s[52:53] op_sel_hi:[1,0]
	v_pk_mul_f32 v[142:143], v[142:143], s[52:53] op_sel_hi:[1,0]
	v_cndmask_b32_e64 v147, v189, v185, s[12:13]
	v_cndmask_b32_e64 v146, v188, v184, s[12:13]
	v_cndmask_b32_e64 v165, v191, v187, s[12:13]
	v_cndmask_b32_e64 v164, v190, v186, s[12:13]
	v_pk_fma_f32 v[104:105], v[104:105], v[146:147], v[140:141]
	v_cmp_gt_i32_e32 vcc, s63, v178
	v_pk_fma_f32 v[106:107], v[106:107], v[164:165], v[142:143]
	v_cvt_pk_bf16_f32 v141, v104, v105
	v_pk_mul_f32 v[146:147], v[180:181], s[52:53] op_sel_hi:[1,0]
	v_cndmask_b32_e32 v105, v189, v185, vcc
	v_cndmask_b32_e32 v104, v188, v184, vcc
	v_cvt_pk_bf16_f32 v117, v106, v107
	v_cndmask_b32_e32 v107, v191, v187, vcc
	v_cndmask_b32_e32 v106, v190, v186, vcc
	v_pk_mul_f32 v[142:143], v[182:183], s[52:53] op_sel_hi:[1,0]
	v_pk_fma_f32 v[100:101], v[100:101], v[104:105], v[146:147]
	v_cmp_gt_i32_e64 s[4:5], s63, v176
	v_pk_fma_f32 v[102:103], v[102:103], v[106:107], v[142:143]
	v_cvt_pk_bf16_f32 v107, v100, v101
	v_pk_mul_f32 v[142:143], v[160:161], s[52:53] op_sel_hi:[1,0]
	v_cndmask_b32_e64 v101, v189, v185, s[4:5]
	v_cndmask_b32_e64 v100, v188, v184, s[4:5]
	v_cvt_pk_bf16_f32 v106, v102, v103
	v_cndmask_b32_e64 v103, v191, v187, s[4:5]
	v_cndmask_b32_e64 v102, v190, v186, s[4:5]
	v_pk_mul_f32 v[104:105], v[162:163], s[52:53] op_sel_hi:[1,0]
	v_pk_fma_f32 v[96:97], v[96:97], v[100:101], v[142:143]
	v_cmp_gt_i32_e64 s[6:7], s63, v174
	v_pk_fma_f32 v[98:99], v[98:99], v[102:103], v[104:105]
	v_cvt_pk_bf16_f32 v102, v96, v97
	v_pk_mul_f32 v[142:143], v[156:157], s[52:53] op_sel_hi:[1,0]
	v_cndmask_b32_e64 v97, v189, v185, s[6:7]
	v_cndmask_b32_e64 v96, v188, v184, s[6:7]
	v_cvt_pk_bf16_f32 v101, v98, v99
	v_cndmask_b32_e64 v99, v191, v187, s[6:7]
	v_cndmask_b32_e64 v98, v190, v186, s[6:7]
	v_pk_mul_f32 v[104:105], v[158:159], s[52:53] op_sel_hi:[1,0]
	v_pk_fma_f32 v[92:93], v[92:93], v[96:97], v[142:143]
	v_cmp_gt_i32_e64 s[8:9], s63, v172
	v_pk_fma_f32 v[94:95], v[94:95], v[98:99], v[104:105]
	v_cvt_pk_bf16_f32 v193, v92, v93
	v_pk_mul_f32 v[98:99], v[152:153], s[52:53] op_sel_hi:[1,0]
	v_cndmask_b32_e64 v93, v189, v185, s[8:9]
	v_cndmask_b32_e64 v92, v188, v184, s[8:9]
	v_cvt_pk_bf16_f32 v195, v94, v95
	v_cndmask_b32_e64 v95, v191, v187, s[8:9]
	v_cndmask_b32_e64 v94, v190, v186, s[8:9]
	v_pk_mul_f32 v[96:97], v[154:155], s[52:53] op_sel_hi:[1,0]
	v_pk_fma_f32 v[16:17], v[16:17], v[92:93], v[98:99]
	v_cmp_gt_i32_e64 s[10:11], s63, v166
	v_pk_fma_f32 v[18:19], v[18:19], v[94:95], v[96:97]
	v_cvt_pk_bf16_f32 v147, v16, v17
	v_pk_mul_f32 v[94:95], v[148:149], s[52:53] op_sel_hi:[1,0]
	v_cndmask_b32_e64 v17, v189, v185, s[10:11]
	v_cndmask_b32_e64 v16, v188, v184, s[10:11]
	v_pk_fma_f32 v[12:13], v[12:13], v[16:17], v[94:95]
	v_cvt_pk_bf16_f32 v146, v18, v19
	v_cndmask_b32_e64 v19, v191, v187, s[10:11]
	v_cndmask_b32_e64 v18, v190, v186, s[10:11]
	v_pk_mul_f32 v[92:93], v[150:151], s[52:53] op_sel_hi:[1,0]
	v_cvt_pk_bf16_f32 v129, v12, v13
	v_or_b32_e32 v12, 4, v168
	v_pk_fma_f32 v[14:15], v[14:15], v[18:19], v[92:93]
	v_and_b32_e32 v140, 0xffff0000, v141
	v_cvt_pk_bf16_f32 v127, v14, v15
	v_readlane_b32 s38, v255, 21
	v_ashrrev_i32_e32 v13, 31, v12
	v_lshlrev_b64 v[16:17], 2, v[12:13]
	v_lshl_add_u64 v[92:93], v[130:131], 0, v[16:17]
	v_lshl_add_u64 v[94:95], v[132:133], 0, v[16:17]
	v_lshl_add_u64 v[96:97], v[138:139], 0, v[16:17]
	v_lshl_add_u64 v[12:13], s[0:1], 0, v[16:17]
	v_lshl_add_u64 v[14:15], s[78:79], 0, v[16:17]
	v_lshl_add_u64 v[18:19], v[0:1], 0, v[16:17]
	v_lshl_add_u64 v[104:105], v[134:135], 0, v[16:17]
	v_lshl_add_u64 v[142:143], v[136:137], 0, v[16:17]
	global_load_dwordx4 v[96:99], v[96:97], off
	s_nop 0
	global_load_dwordx4 v[148:151], v[142:143], off
	global_load_dwordx4 v[152:155], v[104:105], off
	global_load_dwordx4 v[156:159], v[94:95], off
	s_nop 0
	global_load_dwordx4 v[92:95], v[92:93], off
	s_nop 0
	global_load_dwordx4 v[160:163], v[18:19], off
	global_load_dwordx4 v[180:183], v[12:13], off
	global_load_dwordx4 v[184:187], v[14:15], off
	v_lshl_add_u64 v[12:13], s[30:31], 0, v[16:17]
	v_lshl_add_u64 v[16:17], s[36:37], 0, v[16:17]
	global_load_dwordx4 v[12:15], v[12:13], off
	v_readlane_b32 s39, v255, 22
	global_load_dwordx4 v[16:19], v[16:17], off
	s_waitcnt vmcnt(4)
	s_nop 0
	v_pk_mul_f32 v[162:163], v[162:163], s[52:53] op_sel_hi:[1,0]
	s_waitcnt vmcnt(2)
	v_cndmask_b32_e64 v105, v185, v181, s[12:13]
	v_cndmask_b32_e64 v104, v184, v180, s[12:13]
	v_cndmask_b32_e64 v143, v187, v183, s[12:13]
	v_cndmask_b32_e64 v142, v186, v182, s[12:13]
	v_pk_mul_f32 v[160:161], v[160:161], s[52:53] op_sel_hi:[1,0]
	v_pk_fma_f32 v[90:91], v[90:91], v[142:143], v[162:163]
	v_pk_fma_f32 v[88:89], v[88:89], v[104:105], v[160:161]
	v_pk_mul_f32 v[92:93], v[92:93], s[52:53] op_sel_hi:[1,0]
	v_cvt_pk_bf16_f32 v89, v88, v89
	v_cvt_pk_bf16_f32 v88, v90, v91
	v_cndmask_b32_e32 v91, v185, v181, vcc
	v_cndmask_b32_e32 v90, v184, v180, vcc
	v_cndmask_b32_e32 v105, v187, v183, vcc
	v_cndmask_b32_e32 v104, v186, v182, vcc
	v_pk_mul_f32 v[94:95], v[94:95], s[52:53] op_sel_hi:[1,0]
	v_pk_fma_f32 v[84:85], v[84:85], v[90:91], v[92:93]
	v_pk_fma_f32 v[86:87], v[86:87], v[104:105], v[94:95]
	v_cvt_pk_bf16_f32 v95, v84, v85
	v_cndmask_b32_e64 v85, v185, v181, s[4:5]
	v_cndmask_b32_e64 v84, v184, v180, s[4:5]
	v_pk_mul_f32 v[104:105], v[156:157], s[52:53] op_sel_hi:[1,0]
	v_cvt_pk_bf16_f32 v90, v86, v87
	v_cndmask_b32_e64 v87, v187, v183, s[4:5]
	v_cndmask_b32_e64 v86, v186, v182, s[4:5]
	v_pk_mul_f32 v[92:93], v[158:159], s[52:53] op_sel_hi:[1,0]
	v_pk_fma_f32 v[80:81], v[80:81], v[84:85], v[104:105]
	v_pk_fma_f32 v[82:83], v[82:83], v[86:87], v[92:93]
	v_cvt_pk_bf16_f32 v104, v80, v81
	v_cndmask_b32_e64 v81, v185, v181, s[6:7]
	v_cndmask_b32_e64 v80, v184, v180, s[6:7]
	v_pk_mul_f32 v[86:87], v[152:153], s[52:53] op_sel_hi:[1,0]
	v_cvt_pk_bf16_f32 v92, v82, v83
	v_cndmask_b32_e64 v83, v187, v183, s[6:7]
	v_cndmask_b32_e64 v82, v186, v182, s[6:7]
	v_pk_mul_f32 v[84:85], v[154:155], s[52:53] op_sel_hi:[1,0]
	v_pk_fma_f32 v[76:77], v[76:77], v[80:81], v[86:87]
	v_pk_fma_f32 v[78:79], v[78:79], v[82:83], v[84:85]
	v_cvt_pk_bf16_f32 v198, v76, v77
	v_cndmask_b32_e64 v77, v185, v181, s[8:9]
	v_cndmask_b32_e64 v76, v184, v180, s[8:9]
	v_pk_mul_f32 v[82:83], v[148:149], s[52:53] op_sel_hi:[1,0]
	v_cvt_pk_bf16_f32 v100, v78, v79
	v_cndmask_b32_e64 v79, v187, v183, s[8:9]
	v_cndmask_b32_e64 v78, v186, v182, s[8:9]
	v_pk_mul_f32 v[80:81], v[150:151], s[52:53] op_sel_hi:[1,0]
	v_pk_fma_f32 v[28:29], v[28:29], v[76:77], v[82:83]
	v_pk_fma_f32 v[30:31], v[30:31], v[78:79], v[80:81]
	v_cvt_pk_bf16_f32 v148, v28, v29
	v_cndmask_b32_e64 v29, v185, v181, s[10:11]
	v_cndmask_b32_e64 v28, v184, v180, s[10:11]
	v_pk_mul_f32 v[78:79], v[96:97], s[52:53] op_sel_hi:[1,0]
	v_cvt_pk_bf16_f32 v150, v30, v31
	v_cndmask_b32_e64 v31, v187, v183, s[10:11]
	v_pk_fma_f32 v[24:25], v[24:25], v[28:29], v[78:79]
	v_cndmask_b32_e64 v30, v186, v182, s[10:11]
	v_pk_mul_f32 v[76:77], v[98:99], s[52:53] op_sel_hi:[1,0]
	v_cvt_pk_bf16_f32 v169, v24, v25
	v_add_u32_e32 v24, 0x80, v168
	v_pk_fma_f32 v[26:27], v[26:27], v[30:31], v[76:77]
	v_readlane_b32 s40, v255, 23
	v_cvt_pk_bf16_f32 v145, v26, v27
	v_readlane_b32 s41, v255, 24
	v_ashrrev_i32_e32 v25, 31, v24
	v_lshlrev_b64 v[28:29], 2, v[24:25]
	v_lshl_add_u64 v[96:97], v[130:131], 0, v[28:29]
	v_lshl_add_u64 v[98:99], v[132:133], 0, v[28:29]
	v_lshl_add_u64 v[84:85], v[134:135], 0, v[28:29]
	v_lshl_add_u64 v[80:81], v[136:137], 0, v[28:29]
	v_lshl_add_u64 v[76:77], v[138:139], 0, v[28:29]
	v_lshl_add_u64 v[24:25], s[0:1], 0, v[28:29]
	v_lshl_add_u64 v[26:27], s[78:79], 0, v[28:29]
	v_lshl_add_u64 v[30:31], v[0:1], 0, v[28:29]
	global_load_dwordx4 v[76:79], v[76:77], off
	s_nop 0
	global_load_dwordx4 v[80:83], v[80:81], off
	s_nop 0
	global_load_dwordx4 v[84:87], v[84:85], off
	s_nop 0
	global_load_dwordx4 v[152:155], v[98:99], off
	s_nop 0
	global_load_dwordx4 v[96:99], v[96:97], off
	s_nop 0
	global_load_dwordx4 v[156:159], v[30:31], off
	global_load_dwordx4 v[160:163], v[24:25], off
	global_load_dwordx4 v[180:183], v[26:27], off
	v_lshl_add_u64 v[24:25], s[30:31], 0, v[28:29]
	v_lshl_add_u64 v[28:29], s[36:37], 0, v[28:29]
	global_load_dwordx4 v[24:27], v[24:25], off
	v_readlane_b32 s42, v255, 25
	global_load_dwordx4 v[28:31], v[28:29], off
	s_waitcnt vmcnt(4)
	s_nop 0
	v_pk_mul_f32 v[156:157], v[156:157], s[52:53] op_sel_hi:[1,0]
	s_waitcnt vmcnt(2)
	v_cndmask_b32_e64 v143, v181, v161, s[12:13]
	v_cndmask_b32_e64 v142, v180, v160, s[12:13]
	v_cndmask_b32_e64 v165, v183, v163, s[12:13]
	v_cndmask_b32_e64 v164, v182, v162, s[12:13]
	v_pk_mul_f32 v[158:159], v[158:159], s[52:53] op_sel_hi:[1,0]
	v_pk_fma_f32 v[72:73], v[72:73], v[142:143], v[156:157]
	v_pk_fma_f32 v[74:75], v[74:75], v[164:165], v[158:159]
	v_cvt_pk_bf16_f32 v143, v72, v73
	v_cndmask_b32_e32 v73, v181, v161, vcc
	v_cndmask_b32_e32 v72, v180, v160, vcc
	v_pk_mul_f32 v[96:97], v[96:97], s[52:53] op_sel_hi:[1,0]
	v_cvt_pk_bf16_f32 v164, v74, v75
	v_cndmask_b32_e32 v75, v183, v163, vcc
	v_cndmask_b32_e32 v74, v182, v162, vcc
	v_pk_mul_f32 v[98:99], v[98:99], s[52:53] op_sel_hi:[1,0]
	v_pk_fma_f32 v[68:69], v[68:69], v[72:73], v[96:97]
	v_pk_fma_f32 v[70:71], v[70:71], v[74:75], v[98:99]
	v_cvt_pk_bf16_f32 v96, v68, v69
	v_cndmask_b32_e64 v69, v181, v161, s[4:5]
	v_cndmask_b32_e64 v68, v180, v160, s[4:5]
	v_pk_mul_f32 v[74:75], v[152:153], s[52:53] op_sel_hi:[1,0]
	v_cvt_pk_bf16_f32 v91, v70, v71
	v_cndmask_b32_e64 v71, v183, v163, s[4:5]
	v_cndmask_b32_e64 v70, v182, v162, s[4:5]
	v_pk_mul_f32 v[72:73], v[154:155], s[52:53] op_sel_hi:[1,0]
	v_pk_fma_f32 v[64:65], v[64:65], v[68:69], v[74:75]
	v_pk_fma_f32 v[66:67], v[66:67], v[70:71], v[72:73]
	v_cvt_pk_bf16_f32 v94, v64, v65
	v_cndmask_b32_e64 v65, v181, v161, s[6:7]
	v_cndmask_b32_e64 v64, v180, v160, s[6:7]
	v_pk_mul_f32 v[70:71], v[84:85], s[52:53] op_sel_hi:[1,0]
	v_cvt_pk_bf16_f32 v93, v66, v67
	v_cndmask_b32_e64 v67, v183, v163, s[6:7]
	v_cndmask_b32_e64 v66, v182, v162, s[6:7]
	v_pk_mul_f32 v[68:69], v[86:87], s[52:53] op_sel_hi:[1,0]
	v_pk_fma_f32 v[60:61], v[60:61], v[64:65], v[70:71]
	v_pk_fma_f32 v[62:63], v[62:63], v[66:67], v[68:69]
	v_cvt_pk_bf16_f32 v105, v60, v61
	v_cndmask_b32_e64 v61, v181, v161, s[8:9]
	v_cndmask_b32_e64 v60, v180, v160, s[8:9]
	v_pk_mul_f32 v[66:67], v[80:81], s[52:53] op_sel_hi:[1,0]
	v_cvt_pk_bf16_f32 v103, v62, v63
	v_cndmask_b32_e64 v63, v183, v163, s[8:9]
	v_cndmask_b32_e64 v62, v182, v162, s[8:9]
	v_pk_mul_f32 v[64:65], v[82:83], s[52:53] op_sel_hi:[1,0]
	v_pk_fma_f32 v[36:37], v[36:37], v[60:61], v[66:67]
	v_pk_fma_f32 v[38:39], v[38:39], v[62:63], v[64:65]
	v_cvt_pk_bf16_f32 v205, v36, v37
	v_cndmask_b32_e64 v37, v181, v161, s[10:11]
	v_cndmask_b32_e64 v36, v180, v160, s[10:11]
	v_pk_mul_f32 v[62:63], v[76:77], s[52:53] op_sel_hi:[1,0]
	v_cvt_pk_bf16_f32 v203, v38, v39
	v_cndmask_b32_e64 v39, v183, v163, s[10:11]
	v_pk_fma_f32 v[32:33], v[32:33], v[36:37], v[62:63]
	v_cndmask_b32_e64 v38, v182, v162, s[10:11]
	v_pk_mul_f32 v[60:61], v[78:79], s[52:53] op_sel_hi:[1,0]
	v_cvt_pk_bf16_f32 v149, v32, v33
	v_add_u32_e32 v32, 0x84, v168
	v_pk_fma_f32 v[34:35], v[34:35], v[38:39], v[60:61]
	v_lshlrev_b32_e32 v76, 16, v143
	v_cvt_pk_bf16_f32 v151, v34, v35
	v_and_b32_e32 v77, 0xffff0000, v143
	v_ashrrev_i32_e32 v33, 31, v32
	v_lshlrev_b64 v[36:37], 2, v[32:33]
	v_lshl_add_u64 v[66:67], v[138:139], 0, v[36:37]
	v_lshl_add_u64 v[32:33], s[0:1], 0, v[36:37]
	v_lshl_add_u64 v[34:35], s[78:79], 0, v[36:37]
	v_lshl_add_u64 v[0:1], v[0:1], 0, v[36:37]
	v_lshl_add_u64 v[38:39], v[130:131], 0, v[36:37]
	v_lshl_add_u64 v[60:61], v[132:133], 0, v[36:37]
	v_lshl_add_u64 v[62:63], v[134:135], 0, v[36:37]
	v_lshl_add_u64 v[64:65], v[136:137], 0, v[36:37]
	global_load_dwordx4 v[130:133], v[66:67], off
	global_load_dwordx4 v[134:137], v[64:65], off
	global_load_dwordx4 v[152:155], v[62:63], off
	global_load_dwordx4 v[156:159], v[60:61], off
	global_load_dwordx4 v[160:163], v[38:39], off
	global_load_dwordx4 v[80:83], v[0:1], off
	global_load_dwordx4 v[180:183], v[32:33], off
	global_load_dwordx4 v[184:187], v[34:35], off
	v_lshl_add_u64 v[0:1], s[30:31], 0, v[36:37]
	global_load_dwordx4 v[32:35], v[0:1], off
	v_lshl_add_u64 v[0:1], s[36:37], 0, v[36:37]
	global_load_dwordx4 v[36:39], v[0:1], off
	v_lshlrev_b32_e32 v0, 2, v2
	v_lshlrev_b32_e32 v138, 16, v88
	v_xor_b32_e32 v227, 64, v0
	v_xor_b32_e32 v226, 0x80, v0
	v_and_b32_e32 v139, 0xffff0000, v88
	v_mul_f32_e32 v0, v138, v138
	v_lshlrev_b32_e32 v78, 16, v164
	v_and_b32_e32 v79, 0xffff0000, v164
	v_pk_fma_f32 v[62:63], v[138:139], v[138:139], v[0:1] op_sel_hi:[1,1,0]
	s_waitcnt vmcnt(11)
	v_pk_mul_f32 v[64:65], v[26:27], v[78:79]
	v_pk_mul_f32 v[66:67], v[24:25], v[76:77]
	s_waitcnt vmcnt(10)
	v_pk_mul_f32 v[74:75], v[30:31], v[64:65]
	v_add_f32_e32 v62, v66, v67
	v_add_f32_e32 v68, v64, v65
	s_waitcnt vmcnt(4)
	v_pk_mul_f32 v[60:61], v[24:25], v[66:67]
	v_pk_mul_f32 v[84:85], v[28:29], v[66:67]
	v_add_f32_e32 v69, v62, v68
	v_mul_f32_e32 v68, v67, v67
	v_add_f32_e32 v67, v74, v75
	s_waitcnt vmcnt(2)
	v_cndmask_b32_e64 v75, v185, v181, s[12:13]
	v_cndmask_b32_e64 v74, v184, v180, s[12:13]
	v_pk_mul_f32 v[80:81], v[80:81], s[52:53] op_sel_hi:[1,0]
	v_pk_mul_f32 v[0:1], v[26:27], v[64:65]
	v_mul_f32_e32 v62, v64, v64
	v_mul_f32_e32 v64, v65, v65
	v_add_f32_e32 v65, v84, v85
	v_cndmask_b32_e64 v85, v187, v183, s[12:13]
	v_cndmask_b32_e64 v84, v186, v182, s[12:13]
	v_pk_mul_f32 v[82:83], v[82:83], s[52:53] op_sel_hi:[1,0]
	v_pk_fma_f32 v[56:57], v[56:57], v[74:75], v[80:81]
	v_pk_fma_f32 v[58:59], v[58:59], v[84:85], v[82:83]
	v_cvt_pk_bf16_f32 v56, v56, v57
	v_add_f32_e32 v65, v65, v67
	v_cvt_pk_bf16_f32 v57, v58, v59
	v_lshlrev_b32_e32 v80, 16, v56
	v_and_b32_e32 v81, 0xffff0000, v56
	v_lshlrev_b32_e32 v82, 16, v57
	v_and_b32_e32 v83, 0xffff0000, v57
	s_waitcnt vmcnt(1)
	v_pk_mul_f32 v[74:75], v[34:35], v[82:83]
	v_pk_mul_f32 v[84:85], v[32:33], v[80:81]
	s_waitcnt vmcnt(0)
	v_pk_mul_f32 v[98:99], v[38:39], v[74:75]
	v_pk_mul_f32 v[164:165], v[36:37], v[84:85]
	v_add_f32_e32 v67, v84, v85
	v_add_f32_e32 v86, v74, v75
	v_pk_mul_f32 v[56:57], v[34:35], v[74:75]
	v_pk_mul_f32 v[58:59], v[32:33], v[84:85]
	v_add_f32_e32 v67, v67, v86
	v_mul_f32_e32 v86, v84, v84
	v_mul_f32_e32 v88, v85, v85
	v_mul_f32_e32 v84, v75, v75
	v_add_f32_e32 v75, v164, v165
	v_add_f32_e32 v85, v98, v99
	v_cndmask_b32_e32 v99, v185, v181, vcc
	v_cndmask_b32_e32 v98, v184, v180, vcc
	v_cndmask_b32_e32 v165, v187, v183, vcc
	v_cndmask_b32_e32 v164, v186, v182, vcc
	v_pk_mul_f32 v[162:163], v[162:163], s[52:53] op_sel_hi:[1,0]
	v_pk_mul_f32 v[160:161], v[160:161], s[52:53] op_sel_hi:[1,0]
	v_pk_fma_f32 v[54:55], v[54:55], v[164:165], v[162:163]
	v_pk_fma_f32 v[52:53], v[52:53], v[98:99], v[160:161]
	v_cndmask_b32_e64 v99, v187, v183, s[4:5]
	v_cvt_pk_bf16_f32 v53, v52, v53
	v_cvt_pk_bf16_f32 v52, v54, v55
	v_cndmask_b32_e64 v55, v185, v181, s[4:5]
	v_cndmask_b32_e64 v54, v184, v180, s[4:5]
	v_cndmask_b32_e64 v98, v186, v182, s[4:5]
	v_pk_mul_f32 v[158:159], v[158:159], s[52:53] op_sel_hi:[1,0]
	v_pk_mul_f32 v[156:157], v[156:157], s[52:53] op_sel_hi:[1,0]
	v_pk_fma_f32 v[98:99], v[50:51], v[98:99], v[158:159]
	v_pk_fma_f32 v[48:49], v[48:49], v[54:55], v[156:157]
	v_cndmask_b32_e64 v55, v187, v183, s[6:7]
	v_cvt_pk_bf16_f32 v51, v48, v49
	v_cvt_pk_bf16_f32 v50, v98, v99
	v_cndmask_b32_e64 v49, v185, v181, s[6:7]
	v_cndmask_b32_e64 v48, v184, v180, s[6:7]
	v_cndmask_b32_e64 v54, v186, v182, s[6:7]
	v_pk_mul_f32 v[98:99], v[154:155], s[52:53] op_sel_hi:[1,0]
	v_pk_mul_f32 v[152:153], v[152:153], s[52:53] op_sel_hi:[1,0]
	v_pk_fma_f32 v[46:47], v[46:47], v[54:55], v[98:99]
	v_pk_fma_f32 v[44:45], v[44:45], v[48:49], v[152:153]
	v_pk_mul_f32 v[54:55], v[136:137], s[52:53] op_sel_hi:[1,0]
	v_cvt_pk_bf16_f32 v49, v44, v45
	v_cvt_pk_bf16_f32 v48, v46, v47
	v_cndmask_b32_e64 v45, v185, v181, s[8:9]
	v_cndmask_b32_e64 v44, v184, v180, s[8:9]
	v_cndmask_b32_e64 v47, v187, v183, s[8:9]
	v_cndmask_b32_e64 v46, v186, v182, s[8:9]
	v_pk_mul_f32 v[98:99], v[134:135], s[52:53] op_sel_hi:[1,0]
	v_lshlrev_b32_e32 v155, 16, v89
	v_pk_fma_f32 v[42:43], v[42:43], v[46:47], v[54:55]
	v_pk_fma_f32 v[40:41], v[40:41], v[44:45], v[98:99]
	v_lshlrev_b32_e32 v154, 16, v141
	v_mov_b32_e32 v141, v155
	v_and_b32_e32 v157, 0xffff0000, v89
	v_lshlrev_b32_e32 v142, 16, v117
	v_cvt_pk_bf16_f32 v47, v40, v41
	v_cvt_pk_bf16_f32 v46, v42, v43
	v_cndmask_b32_e64 v41, v187, v183, s[10:11]
	v_cndmask_b32_e64 v40, v186, v182, s[10:11]
	v_pk_mul_f32 v[42:43], v[132:133], s[52:53] op_sel_hi:[1,0]
	v_and_b32_e32 v156, 0xffff0000, v117
	v_mov_b32_e32 v143, v157
	v_pk_mul_f32 v[136:137], v[154:155], v[154:155]
	v_pk_mul_f32 v[152:153], v[140:141], v[140:141]
	v_pk_mul_f32 v[98:99], v[130:131], s[52:53] op_sel_hi:[1,0]
	v_pk_fma_f32 v[130:131], v[22:23], v[40:41], v[42:43]
	v_mov_b32_e32 v22, v142
	v_mov_b32_e32 v23, v156
	v_mov_b32_e32 v40, v154
	v_mov_b32_e32 v41, v140
	v_pk_mul_f32 v[158:159], v[142:143], v[142:143]
	v_pk_mul_f32 v[160:161], v[156:157], v[156:157]
	v_pk_mov_b32 v[182:183], v[154:155], v[136:137] op_sel:[1,0]
	v_pk_mov_b32 v[152:153], v[156:157], v[152:153] op_sel:[1,0]
	v_pk_mul_f32 v[22:23], v[6:7], v[22:23]
	v_pk_mul_f32 v[40:41], v[4:5], v[40:41]
	v_pk_add_f32 v[152:153], v[182:183], v[152:153]
	v_mov_b32_e32 v182, v138
	v_mov_b32_e32 v183, v158
	v_pk_mov_b32 v[158:159], v[138:139], v[160:161] op_sel:[1,0]
	v_add_f32_e32 v75, v75, v85
	v_pk_mul_f32 v[54:55], v[4:5], v[40:41]
	v_pk_mul_f32 v[132:133], v[10:11], v[22:23]
	v_pk_mul_f32 v[134:135], v[8:9], v[40:41]
	v_add_f32_e32 v85, v40, v41
	v_mul_f32_e32 v162, v40, v40
	v_mul_f32_e32 v40, v23, v23
	v_pk_add_f32 v[158:159], v[182:183], v[158:159]
	v_cndmask_b32_e64 v45, v185, v181, s[10:11]
	v_cndmask_b32_e64 v44, v184, v180, s[10:11]
	v_pk_mul_f32 v[42:43], v[6:7], v[22:23]
	v_add_f32_e32 v87, v22, v23
	v_pk_fma_f32 v[180:181], v[22:23], v[22:23], v[40:41] op_sel_hi:[1,1,0]
	v_add_f32_e32 v22, v134, v135
	v_add_f32_e32 v23, v132, v133
	v_pk_add_f32 v[152:153], v[152:153], v[158:159]
	v_pk_add_f32 v[158:159], v[154:155], v[140:141]
	v_add_f32_e32 v22, v22, v23
	v_mov_b32_e32 v159, v137
	v_pk_add_f32 v[136:137], v[156:157], v[142:143]
	v_add_f32_e32 v85, v85, v87
	v_add_f32_e32 v87, 0, v22
	v_mov_b32_e32 v22, v155
	v_mov_b32_e32 v23, v157
	v_mov_b32_e32 v137, v161
	v_mul_f32_e32 v164, v41, v41
	v_pk_mul_f32 v[22:23], v[12:13], v[22:23]
	v_pk_mul_f32 v[40:41], v[14:15], v[138:139]
	v_pk_add_f32 v[136:137], v[158:159], v[136:137]
	v_mov_b32_e32 v117, v63
	v_pk_mul_f32 v[132:133], v[18:19], v[40:41]
	v_pk_mul_f32 v[134:135], v[16:17], v[22:23]
	v_pk_add_f32 v[136:137], v[136:137], v[116:117]
	v_add_f32_e32 v163, v54, v55
	v_pk_mul_f32 v[54:55], v[12:13], v[22:23]
	v_pk_add_f32 v[136:137], v[152:153], v[136:137]
	v_add_f32_e32 v63, v22, v23
	v_add_f32_e32 v89, v40, v41
	v_mul_f32_e32 v152, v22, v22
	v_mul_f32_e32 v158, v23, v23
	v_add_f32_e32 v22, v134, v135
	v_add_f32_e32 v23, v132, v133
	v_pk_mul_f32 v[72:73], v[76:77], v[76:77]
	v_pk_mul_f32 v[70:71], v[78:79], v[78:79]
	v_add_f32_e32 v85, 0, v85
	v_add_f32_e32 v63, v63, v89
	v_add_f32_e32 v22, v22, v23
	v_add_f32_e32 v165, v42, v43
	v_pk_mul_f32 v[42:43], v[14:15], v[40:41]
	v_add_f32_e32 v63, v85, v63
	v_mul_f32_e32 v160, v40, v40
	v_mul_f32_e32 v182, v41, v41
	v_add_f32_e32 v85, v87, v22
	v_mov_b32_e32 v22, v76
	v_mov_b32_e32 v23, v72
	v_mov_b32_e32 v72, v77
	v_mov_b32_e32 v40, v78
	v_mov_b32_e32 v41, v70
	v_mov_b32_e32 v70, v79
	v_pk_mul_f32 v[188:189], v[80:81], v[80:81]
	v_pk_mul_f32 v[190:191], v[82:83], v[82:83]
	v_pk_add_f32 v[22:23], v[22:23], v[72:73]
	v_pk_add_f32 v[40:41], v[40:41], v[70:71]
	v_mov_b32_e32 v70, v82
	v_pk_add_f32 v[22:23], v[22:23], v[40:41]
	v_mov_b32_e32 v40, v80
	v_mov_b32_e32 v41, v188
	v_mov_b32_e32 v188, v81
	v_mov_b32_e32 v71, v190
	v_mov_b32_e32 v190, v83
	v_pk_add_f32 v[40:41], v[40:41], v[188:189]
	v_pk_add_f32 v[70:71], v[70:71], v[190:191]
	v_add_f32_e32 v65, v85, v65
	v_mul_f32_e32 v74, v74, v74
	v_pk_add_f32 v[40:41], v[40:41], v[70:71]
	v_add_f32_e32 v71, v65, v75
	v_mov_b32_e32 v87, v58
	v_mov_b32_e32 v89, v59
	v_mov_b32_e32 v75, v56
	v_mov_b32_e32 v85, v57
	v_add_f32_e32 v63, v63, v69
	v_pk_add_f32 v[58:59], v[86:87], v[88:89]
	v_pk_add_f32 v[56:57], v[74:75], v[84:85]
	v_mov_b32_e32 v153, v54
	v_mov_b32_e32 v159, v55
	v_mov_b32_e32 v161, v42
	v_mov_b32_e32 v183, v43
	v_mul_f32_e32 v66, v66, v66
	v_add_f32_e32 v70, v63, v67
	v_mov_b32_e32 v67, v60
	v_mov_b32_e32 v69, v61
	v_mov_b32_e32 v63, v0
	v_mov_b32_e32 v65, v1
	v_pk_add_f32 v[56:57], v[58:59], v[56:57]
	v_pk_add_f32 v[58:59], v[162:163], v[164:165]
	v_mov_b32_e32 v181, v116
	v_pk_add_f32 v[54:55], v[152:153], v[158:159]
	v_pk_add_f32 v[42:43], v[160:161], v[182:183]
	v_pk_add_f32 v[60:61], v[66:67], v[68:69]
	v_pk_add_f32 v[0:1], v[62:63], v[64:65]
	v_pk_add_f32 v[58:59], v[58:59], v[180:181]
	v_pk_add_f32 v[42:43], v[54:55], v[42:43]
	v_pk_add_f32 v[0:1], v[60:61], v[0:1]
	v_pk_add_f32 v[42:43], v[58:59], v[42:43]
	v_pk_add_f32 v[22:23], v[136:137], v[22:23]
	v_pk_add_f32 v[0:1], v[42:43], v[0:1]
	v_pk_add_f32 v[22:23], v[22:23], v[40:41]
	v_pk_add_f32 v[0:1], v[0:1], v[56:57]
	ds_bpermute_b32 v40, v227, v22
	ds_bpermute_b32 v41, v227, v23
	ds_bpermute_b32 v72, v227, v70
	ds_bpermute_b32 v42, v227, v0
	ds_bpermute_b32 v43, v227, v1
	ds_bpermute_b32 v56, v227, v71
	s_waitcnt lgkmcnt(4)
	v_pk_add_f32 v[22:23], v[22:23], v[40:41]
	s_waitcnt lgkmcnt(3)
	v_add_f32_e32 v54, v70, v72
	ds_bpermute_b32 v40, v226, v22
	s_waitcnt lgkmcnt(2)
	v_pk_add_f32 v[0:1], v[0:1], v[42:43]
	s_waitcnt lgkmcnt(1)
	v_add_f32_e32 v56, v71, v56
	ds_bpermute_b32 v41, v226, v23
	ds_bpermute_b32 v55, v226, v54
	ds_bpermute_b32 v42, v226, v0
	ds_bpermute_b32 v43, v226, v1
	ds_bpermute_b32 v57, v226, v56
	v_cmp_gt_u32_e32 vcc, 16, v2
	v_readlane_b32 s43, v255, 26
	v_readlane_b32 s44, v255, 27
	v_readlane_b32 s45, v255, 28
	v_readlane_b32 s46, v255, 29
	v_readlane_b32 s47, v255, 30
	v_readlane_b32 s48, v255, 31
	v_readlane_b32 s49, v255, 32
	v_readlane_b32 s50, v255, 33
	v_readlane_b32 s51, v255, 34
	v_pk_fma_f32 v[20:21], v[20:21], v[44:45], v[98:99]
	s_nop 0
	v_cvt_pk_bf16_f32 v45, v20, v21
	v_cvt_pk_bf16_f32 v44, v130, v131
	s_and_saveexec_b64 s[0:1], vcc
	s_cbranch_execz .LBB0_2300
	s_add_i32 s4, s15, 0
	s_waitcnt lgkmcnt(0)
	v_add_f32_e32 v58, v56, v57
	v_pk_add_f32 v[56:57], v[0:1], v[42:43]
	v_lshl_add_u32 v0, v144, 7, s4
	v_add_f32_e32 v42, v54, v55
	v_pk_add_f32 v[40:41], v[22:23], v[40:41]
	v_add_u32_e32 v0, 0x20000, v0
	v_mov_b32_e32 v43, v116
	v_mov_b32_e32 v59, v116
	ds_write_b128 v0, v[40:43]
	ds_write_b128 v0, v[56:59] offset:16

.LBB0_2451:
	s_mov_b32 s0, 0
	s_mov_b32 s1, 0
	s_mov_b32 s4, 0
	s_mov_b32 s5, 0
	s_mov_b32 s25, s92
	s_mov_b32 s80, s35
	v_mbcnt_lo_u32_b32 v2, -1, 0
	v_mbcnt_hi_u32_b32 v2, -1, v2
	s_mul_i32 s24, s80, 48
	v_and_or_b32 v127, v2, 15, s24
	s_mul_i32 s23, s22, 0xc0
	s_lshl_b32 s81, s25, 5
	v_ashrrev_i32_e32 v0, 1, v2
	s_lshl_b32 s0, s14, 8
	v_add_u32_e32 v146, s23, v127
	v_and_b32_e32 v0, -8, v0
	s_add_i32 s75, s81, s0
	v_add_u32_e32 v154, s75, v0
	v_lshlrev_b32_e32 v0, 1, v146
	v_readlane_b32 s0, v254, 25
	v_ashrrev_i32_e32 v1, 31, v0
	v_readlane_b32 s1, v254, 26
	v_add_u32_e32 v6, 32, v0
	v_add_u32_e32 v138, 0x60, v146
	v_lshl_add_u64 v[4:5], v[0:1], 2, s[0:1]
	v_add_u32_e32 v0, 64, v0
	v_ashrrev_i32_e32 v1, 31, v0
	v_lshlrev_b32_e32 v8, 1, v138
	v_mov_b32_e32 v140, 2.0
	v_mov_b32_e32 v126, 0x3a800000
	v_ashrrev_i32_e32 v7, 31, v6
	v_lshl_add_u64 v[0:1], v[0:1], 2, s[0:1]
	v_ashrrev_i32_e32 v9, 31, v8
	v_lshl_add_u64 v[6:7], v[6:7], 2, s[0:1]
	v_lshl_add_u64 v[10:11], v[8:9], 2, s[0:1]
	global_load_dwordx2 v[136:137], v[4:5], off
	global_load_dwordx2 v[134:135], v[6:7], off
	global_load_dwordx2 v[132:133], v[0:1], off
	global_load_dwordx2 v[130:131], v[10:11], off
	v_add_u32_e32 v0, 32, v8
	v_add_u32_e32 v4, 64, v8
	v_ashrrev_i32_e32 v1, 31, v0
	v_ashrrev_i32_e32 v5, 31, v4
	v_lshl_add_u64 v[0:1], v[0:1], 2, s[0:1]
	v_lshl_add_u64 v[4:5], v[4:5], 2, s[0:1]
	s_add_i32 s0, s23, 0xfffff000
	s_add_i32 s1, s23, 0xfffff0bf
	s_lshr_b32 s0, s0, 12
	s_lshr_b32 s1, s1, 12
	global_load_dwordx2 v[128:129], v[0:1], off
	s_nop 0
	global_load_dwordx2 v[0:1], v[4:5], off
	v_mov_b32_e32 v4, v154
	s_add_i32 s0, s0, 1
	s_add_i32 s1, s1, 1
	v_ashrrev_i32_e32 v147, 31, v146
	v_ashrrev_i32_e32 v5, 31, v4
	v_add_u32_e32 v148, 16, v146
	v_add_u32_e32 v172, 32, v146
	v_ashrrev_i32_e32 v139, 31, v138
	s_cmp_gt_i32 s22, 20
	v_lshl_add_u64 v[6:7], v[4:5], 1, s[58:59]
	v_lshlrev_b64 v[162:163], 11, v[146:147]
	v_ashrrev_i32_e32 v149, 31, v148
	v_ashrrev_i32_e32 v173, 31, v172
	v_lshlrev_b64 v[156:157], 11, v[138:139]
	s_cselect_b32 s1, s1, 0
	v_lshl_add_u64 v[8:9], v[6:7], 0, v[162:163]
	v_lshlrev_b64 v[160:161], 11, v[148:149]
	v_lshlrev_b64 v[158:159], 11, v[172:173]
	v_lshl_add_u64 v[144:145], v[6:7], 0, v[156:157]
	s_lshl_b32 s4, s1, 12
	v_lshl_add_u64 v[10:11], v[6:7], 0, v[160:161]
	v_lshl_add_u64 v[142:143], v[6:7], 0, v[158:159]
	global_load_dwordx2 v[174:175], v[8:9], off
	global_load_dword v164, v[8:9], off offset:256
	global_load_dwordx2 v[180:181], v[10:11], off
	global_load_dword v164, v[10:11], off offset:256
	global_load_dwordx2 v[182:183], v[142:143], off
	global_load_dword v164, v[142:143], off offset:256
	global_load_dwordx2 v[188:189], v[144:145], off
	global_load_dword v164, v[144:145], off offset:256
	v_add_u32_e32 v144, 0x70, v146
	s_cmp_gt_i32 s22, 21
	v_ashrrev_i32_e32 v145, 31, v144
	v_add_u32_e32 v142, 0x80, v146
	s_cselect_b32 s0, s0, 0
	v_lshlrev_b64 v[152:153], 11, v[144:145]
	v_ashrrev_i32_e32 v143, 31, v142
	s_cmp_lg_u32 s1, s0
	s_mul_i32 s36, s0, 0x1800
	v_readlane_b32 s40, v255, 3
	v_lshl_add_u64 v[8:9], v[6:7], 0, v[152:153]
	v_lshlrev_b64 v[150:151], 11, v[142:143]
	s_cselect_b32 s15, s4, 0x7fffffff
	s_lshl_b64 s[18:19], s[36:37], 2
	v_readlane_b32 s41, v255, 4
	v_readlane_b32 s42, v255, 5
	v_readlane_b32 s43, v255, 6
	v_readlane_b32 s44, v255, 7
	v_readlane_b32 s45, v255, 8
	v_readlane_b32 s46, v255, 9
	v_readlane_b32 s47, v255, 10
	v_readlane_b32 s48, v255, 11
	v_readlane_b32 s49, v255, 12
	v_readlane_b32 s50, v255, 13
	v_readlane_b32 s51, v255, 14
	v_readlane_b32 s52, v255, 15
	v_readlane_b32 s53, v255, 16
	v_readlane_b32 s54, v255, 17
	v_readlane_b32 s55, v255, 18
	v_lshl_add_u64 v[6:7], v[6:7], 0, v[150:151]
	global_load_dwordx2 v[190:191], v[8:9], off
	global_load_dword v164, v[8:9], off offset:256
	global_load_dwordx2 v[192:193], v[6:7], off
	global_load_dword v164, v[6:7], off offset:256
	s_mul_i32 s4, s1, 0x1800
	s_mov_b32 s5, s37
	v_lshlrev_b64 v[8:9], 2, v[4:5]
	s_add_u32 s0, s88, s18
	s_mov_b64 s[30:31], s[54:55]
	v_readlane_b32 s40, v255, 19
	s_addc_u32 s1, s89, s19
	s_lshl_b64 s[16:17], s[4:5], 2
	v_lshl_add_u64 v[6:7], s[30:31], 0, v[8:9]
	v_readlane_b32 s41, v255, 20
	s_add_u32 s20, s88, s16
	global_load_dwordx4 v[164:167], v[6:7], off
	v_lshl_add_u64 v[6:7], s[40:41], 0, v[8:9]
	v_lshl_add_u64 v[4:5], s[0:1], 0, v[8:9]
	s_addc_u32 s21, s89, s17
	global_load_dwordx4 v[168:171], v[6:7], off
	v_lshl_add_u64 v[6:7], s[20:21], 0, v[8:9]
	global_load_dwordx4 v[176:179], v[4:5], off
	global_load_dwordx4 v[184:187], v[6:7], off
	v_readlane_b32 s46, v255, 25
	v_readlane_b32 s47, v255, 26
	v_readlane_b32 s48, v255, 27
	v_readlane_b32 s49, v255, 28
	v_lshl_add_u64 v[4:5], s[46:47], 0, v[8:9]
	global_load_dwordx4 v[4:7], v[4:5], off
	v_lshl_add_u64 v[8:9], s[48:49], 0, v[8:9]
	global_load_dwordx4 v[8:11], v[8:9], off
	s_waitcnt vmcnt(0)
	s_nop 0
	v_lshlrev_b32_e32 v117, 16, v174
	v_and_b32_e32 v139, 0xffff0000, v174
	v_lshlrev_b32_e32 v141, 16, v175
	v_and_b32_e32 v143, 0xffff0000, v175
	v_lshlrev_b32_e32 v145, 16, v180
	v_and_b32_e32 v149, 0xffff0000, v180
	v_lshlrev_b32_e32 v155, 16, v181
	v_and_b32_e32 v173, 0xffff0000, v181
	v_sub_f32_e32 v175, v143, v136
	v_sub_f32_e32 v174, v141, v136
	v_sub_f32_e32 v181, v139, v136
	v_sub_f32_e32 v180, v117, v136
	v_pk_mul_f32 v[180:181], v[136:137], v[180:181] op_sel:[1,0]
	v_pk_mul_f32 v[174:175], v[136:137], v[174:175] op_sel:[1,0]
	v_cmp_gt_i32_e64 s[12:13], s15, v146
	v_pk_fma_f32 v[174:175], v[166:167], v[174:175], v[170:171]
	v_pk_fma_f32 v[180:181], v[164:165], v[180:181], v[168:169]
	v_lshlrev_b32_e32 v194, 16, v182
	v_and_b32_e32 v195, 0xffff0000, v182
	v_lshlrev_b32_e32 v196, 16, v183
	v_and_b32_e32 v197, 0xffff0000, v183
	v_cndmask_b32_e64 v147, v185, v177, s[12:13]
	v_cndmask_b32_e64 v146, v184, v176, s[12:13]
	v_cndmask_b32_e64 v183, v187, v179, s[12:13]
	v_cndmask_b32_e64 v182, v186, v178, s[12:13]
	v_pk_mul_f32 v[180:181], v[180:181], s[70:71] op_sel_hi:[1,0]
	v_pk_mul_f32 v[174:175], v[174:175], s[70:71] op_sel_hi:[1,0]
	v_pk_fma_f32 v[104:105], v[104:105], v[146:147], v[180:181]
	v_pk_fma_f32 v[174:175], v[106:107], v[182:183], v[174:175]
	v_cvt_pk_bf16_f32 v107, v104, v105
	v_sub_f32_e32 v147, v173, v134
	v_cvt_pk_bf16_f32 v105, v174, v175
	v_sub_f32_e32 v175, v149, v134
	v_sub_f32_e32 v174, v145, v134
	v_sub_f32_e32 v146, v155, v134
	v_pk_mul_f32 v[174:175], v[134:135], v[174:175] op_sel:[1,0]
	v_pk_mul_f32 v[146:147], v[134:135], v[146:147] op_sel:[1,0]
	v_pk_fma_f32 v[174:175], v[164:165], v[174:175], v[168:169]
	v_cmp_gt_i32_e32 vcc, s15, v148
	v_pk_fma_f32 v[146:147], v[166:167], v[146:147], v[170:171]
	v_pk_mul_f32 v[174:175], v[174:175], s[70:71] op_sel_hi:[1,0]
	v_cndmask_b32_e32 v149, v185, v177, vcc
	v_cndmask_b32_e32 v148, v184, v176, vcc
	v_cndmask_b32_e32 v181, v187, v179, vcc
	v_cndmask_b32_e32 v180, v186, v178, vcc
	v_pk_mul_f32 v[146:147], v[146:147], s[70:71] op_sel_hi:[1,0]
	v_pk_fma_f32 v[100:101], v[100:101], v[148:149], v[174:175]
	v_pk_fma_f32 v[102:103], v[102:103], v[180:181], v[146:147]
	v_cvt_pk_bf16_f32 v175, v100, v101
	v_sub_f32_e32 v101, v197, v132
	v_sub_f32_e32 v100, v196, v132
	v_cvt_pk_bf16_f32 v173, v102, v103
	v_sub_f32_e32 v103, v195, v132
	v_sub_f32_e32 v102, v194, v132
	v_pk_mul_f32 v[100:101], v[132:133], v[100:101] op_sel:[1,0]
	v_pk_mul_f32 v[102:103], v[132:133], v[102:103] op_sel:[1,0]
	v_pk_fma_f32 v[100:101], v[166:167], v[100:101], v[170:171]
	v_cmp_gt_i32_e64 s[4:5], s15, v172
	v_pk_fma_f32 v[102:103], v[164:165], v[102:103], v[168:169]
	v_pk_mul_f32 v[100:101], v[100:101], s[70:71] op_sel_hi:[1,0]
	v_cndmask_b32_e64 v149, v187, v179, s[4:5]
	v_cndmask_b32_e64 v148, v186, v178, s[4:5]
	v_lshlrev_b32_e32 v198, 16, v188
	v_and_b32_e32 v188, 0xffff0000, v188
	v_cndmask_b32_e64 v147, v185, v177, s[4:5]
	v_cndmask_b32_e64 v146, v184, v176, s[4:5]
	v_pk_mul_f32 v[102:103], v[102:103], s[70:71] op_sel_hi:[1,0]
	v_pk_fma_f32 v[98:99], v[98:99], v[148:149], v[100:101]
	v_lshlrev_b32_e32 v199, 16, v189
	v_and_b32_e32 v189, 0xffff0000, v189
	v_pk_fma_f32 v[96:97], v[96:97], v[146:147], v[102:103]
	v_cmp_gt_i32_e64 s[6:7], s15, v138
	v_cvt_pk_bf16_f32 v183, v96, v97
	v_cvt_pk_bf16_f32 v182, v98, v99
	v_sub_f32_e32 v99, v188, v130
	v_sub_f32_e32 v98, v198, v130
	v_sub_f32_e32 v97, v189, v130
	v_sub_f32_e32 v96, v199, v130
	v_pk_mul_f32 v[98:99], v[130:131], v[98:99] op_sel:[1,0]
	v_pk_mul_f32 v[96:97], v[130:131], v[96:97] op_sel:[1,0]
	v_pk_fma_f32 v[98:99], v[164:165], v[98:99], v[168:169]
	v_pk_fma_f32 v[96:97], v[166:167], v[96:97], v[170:171]
	v_cndmask_b32_e64 v101, v185, v177, s[6:7]
	v_cndmask_b32_e64 v100, v184, v176, s[6:7]
	v_pk_mul_f32 v[98:99], v[98:99], s[70:71] op_sel_hi:[1,0]
	v_lshlrev_b32_e32 v201, 16, v191
	v_and_b32_e32 v191, 0xffff0000, v191
	v_cndmask_b32_e64 v103, v187, v179, s[6:7]
	v_cndmask_b32_e64 v102, v186, v178, s[6:7]
	v_pk_mul_f32 v[96:97], v[96:97], s[70:71] op_sel_hi:[1,0]
	v_pk_fma_f32 v[92:93], v[92:93], v[100:101], v[98:99]
	v_lshlrev_b32_e32 v200, 16, v190
	v_and_b32_e32 v190, 0xffff0000, v190
	v_pk_fma_f32 v[94:95], v[94:95], v[102:103], v[96:97]
	v_cvt_pk_bf16_f32 v189, v92, v93
	v_sub_f32_e32 v93, v191, v128
	v_sub_f32_e32 v92, v201, v128
	v_cvt_pk_bf16_f32 v149, v94, v95
	v_sub_f32_e32 v95, v190, v128
	v_sub_f32_e32 v94, v200, v128
	v_pk_mul_f32 v[92:93], v[128:129], v[92:93] op_sel:[1,0]
	v_pk_mul_f32 v[94:95], v[128:129], v[94:95] op_sel:[1,0]
	v_pk_fma_f32 v[92:93], v[166:167], v[92:93], v[170:171]
	v_cmp_gt_i32_e64 s[8:9], s15, v144
	v_pk_fma_f32 v[94:95], v[164:165], v[94:95], v[168:169]
	v_pk_mul_f32 v[92:93], v[92:93], s[70:71] op_sel_hi:[1,0]
	v_cndmask_b32_e64 v99, v187, v179, s[8:9]
	v_cndmask_b32_e64 v98, v186, v178, s[8:9]
	v_lshlrev_b32_e32 v202, 16, v192
	v_and_b32_e32 v192, 0xffff0000, v192
	v_cndmask_b32_e64 v97, v185, v177, s[8:9]
	v_cndmask_b32_e64 v96, v184, v176, s[8:9]
	v_pk_mul_f32 v[94:95], v[94:95], s[70:71] op_sel_hi:[1,0]
	v_pk_fma_f32 v[18:19], v[18:19], v[98:99], v[92:93]
	v_pk_fma_f32 v[16:17], v[16:17], v[96:97], v[94:95]
	v_lshlrev_b32_e32 v203, 16, v193
	v_cvt_pk_bf16_f32 v147, v16, v17
	v_cvt_pk_bf16_f32 v146, v18, v19
	v_sub_f32_e32 v19, v192, v0
	v_sub_f32_e32 v18, v202, v0
	v_and_b32_e32 v193, 0xffff0000, v193
	v_pk_mul_f32 v[18:19], v[0:1], v[18:19] op_sel:[1,0]
	v_sub_f32_e32 v17, v193, v0
	v_sub_f32_e32 v16, v203, v0
	v_pk_fma_f32 v[18:19], v[164:165], v[18:19], v[168:169]
	v_cmp_gt_i32_e64 s[10:11], s15, v142
	v_pk_mul_f32 v[16:17], v[0:1], v[16:17] op_sel:[1,0]
	v_pk_mul_f32 v[18:19], v[18:19], s[70:71] op_sel_hi:[1,0]
	v_cndmask_b32_e64 v93, v185, v177, s[10:11]
	v_cndmask_b32_e64 v92, v184, v176, s[10:11]
	v_pk_fma_f32 v[16:17], v[166:167], v[16:17], v[170:171]
	v_pk_fma_f32 v[12:13], v[12:13], v[92:93], v[18:19]
	v_cndmask_b32_e64 v95, v187, v179, s[10:11]
	v_cndmask_b32_e64 v94, v186, v178, s[10:11]
	v_pk_mul_f32 v[16:17], v[16:17], s[70:71] op_sel_hi:[1,0]
	v_cvt_pk_bf16_f32 v155, v12, v13
	v_or_b32_e32 v12, 4, v154
	v_pk_fma_f32 v[14:15], v[14:15], v[94:95], v[16:17]
	v_readlane_b32 s42, v255, 21
	v_cvt_pk_bf16_f32 v141, v14, v15
	v_readlane_b32 s43, v255, 22
	v_ashrrev_i32_e32 v13, 31, v12
	v_lshl_add_u64 v[14:15], v[12:13], 1, s[58:59]
	v_lshl_add_u64 v[16:17], v[14:15], 0, v[162:163]
	v_lshl_add_u64 v[92:93], v[14:15], 0, v[158:159]
	v_lshl_add_u64 v[94:95], v[14:15], 0, v[156:157]
	v_lshl_add_u64 v[18:19], v[14:15], 0, v[160:161]
	global_load_dwordx2 v[138:139], v[16:17], off
	global_load_dwordx2 v[168:169], v[18:19], off
	s_nop 0
	global_load_dwordx2 v[92:93], v[92:93], off
	s_nop 0
	global_load_dwordx2 v[94:95], v[94:95], off
	v_lshl_add_u64 v[16:17], v[14:15], 0, v[152:153]
	v_lshl_add_u64 v[14:15], v[14:15], 0, v[150:151]
	global_load_dwordx2 v[170:171], v[16:17], off
	global_load_dwordx2 v[176:177], v[14:15], off
	v_lshlrev_b64 v[16:17], 2, v[12:13]
	v_lshl_add_u64 v[18:19], s[30:31], 0, v[16:17]
	global_load_dwordx4 v[96:99], v[18:19], off
	v_lshl_add_u64 v[18:19], s[40:41], 0, v[16:17]
	v_lshl_add_u64 v[12:13], s[0:1], 0, v[16:17]
	v_lshl_add_u64 v[14:15], s[20:21], 0, v[16:17]
	global_load_dwordx4 v[100:103], v[18:19], off
	global_load_dwordx4 v[142:145], v[12:13], off
	global_load_dwordx4 v[164:167], v[14:15], off
	v_lshl_add_u64 v[12:13], s[46:47], 0, v[16:17]
	v_lshl_add_u64 v[16:17], s[48:49], 0, v[16:17]
	global_load_dwordx4 v[12:15], v[12:13], off
	v_readlane_b32 s44, v255, 23
	global_load_dwordx4 v[16:19], v[16:17], off
	s_waitcnt vmcnt(6)
	s_nop 0
	v_lshlrev_b32_e32 v104, 16, v138
	v_and_b32_e32 v106, 0xffff0000, v138
	v_lshlrev_b32_e32 v117, 16, v139
	v_and_b32_e32 v138, 0xffff0000, v139
	v_lshlrev_b32_e32 v179, 16, v92
	v_and_b32_e32 v180, 0xffff0000, v92
	v_lshlrev_b32_e32 v181, 16, v93
	v_and_b32_e32 v184, 0xffff0000, v93
	v_lshlrev_b32_e32 v186, 16, v94
	v_and_b32_e32 v187, 0xffff0000, v94
	v_lshlrev_b32_e32 v188, 16, v95
	v_and_b32_e32 v190, 0xffff0000, v95
	v_sub_f32_e32 v93, v138, v136
	v_sub_f32_e32 v92, v117, v136
	v_sub_f32_e32 v95, v106, v136
	v_sub_f32_e32 v94, v104, v136
	v_pk_mul_f32 v[94:95], v[136:137], v[94:95] op_sel:[1,0]
	v_pk_mul_f32 v[92:93], v[136:137], v[92:93] op_sel:[1,0]
	s_waitcnt vmcnt(4)
	v_pk_fma_f32 v[94:95], v[96:97], v[94:95], v[100:101]
	v_pk_fma_f32 v[92:93], v[98:99], v[92:93], v[102:103]
	v_lshlrev_b32_e32 v148, 16, v168
	v_and_b32_e32 v172, 0xffff0000, v168
	v_lshlrev_b32_e32 v174, 16, v169
	v_and_b32_e32 v178, 0xffff0000, v169
	s_waitcnt vmcnt(2)
	v_cndmask_b32_e64 v139, v165, v143, s[12:13]
	v_cndmask_b32_e64 v138, v164, v142, s[12:13]
	v_cndmask_b32_e64 v169, v167, v145, s[12:13]
	v_cndmask_b32_e64 v168, v166, v144, s[12:13]
	v_pk_mul_f32 v[94:95], v[94:95], s[70:71] op_sel_hi:[1,0]
	v_pk_mul_f32 v[92:93], v[92:93], s[70:71] op_sel_hi:[1,0]
	v_pk_fma_f32 v[88:89], v[88:89], v[138:139], v[94:95]
	v_pk_fma_f32 v[90:91], v[90:91], v[168:169], v[92:93]
	v_sub_f32_e32 v93, v172, v134
	v_sub_f32_e32 v92, v148, v134
	v_cvt_pk_bf16_f32 v95, v88, v89
	v_cvt_pk_bf16_f32 v88, v90, v91
	v_sub_f32_e32 v91, v178, v134
	v_sub_f32_e32 v90, v174, v134
	v_pk_mul_f32 v[92:93], v[134:135], v[92:93] op_sel:[1,0]
	v_pk_mul_f32 v[90:91], v[134:135], v[90:91] op_sel:[1,0]
	v_pk_fma_f32 v[92:93], v[96:97], v[92:93], v[100:101]
	v_pk_fma_f32 v[90:91], v[98:99], v[90:91], v[102:103]
	v_cndmask_b32_e32 v139, v165, v143, vcc
	v_cndmask_b32_e32 v138, v164, v142, vcc
	v_pk_mul_f32 v[92:93], v[92:93], s[70:71] op_sel_hi:[1,0]
	v_cndmask_b32_e32 v169, v167, v145, vcc
	v_cndmask_b32_e32 v168, v166, v144, vcc
	v_pk_mul_f32 v[90:91], v[90:91], s[70:71] op_sel_hi:[1,0]
	v_pk_fma_f32 v[84:85], v[84:85], v[138:139], v[92:93]
	v_pk_fma_f32 v[86:87], v[86:87], v[168:169], v[90:91]
	v_cvt_pk_bf16_f32 v178, v84, v85
	v_sub_f32_e32 v85, v184, v132
	v_sub_f32_e32 v84, v181, v132
	v_lshlrev_b32_e32 v193, 16, v171
	v_and_b32_e32 v194, 0xffff0000, v171
	v_cvt_pk_bf16_f32 v171, v86, v87
	v_sub_f32_e32 v87, v180, v132
	v_sub_f32_e32 v86, v179, v132
	v_pk_mul_f32 v[84:85], v[132:133], v[84:85] op_sel:[1,0]
	v_pk_mul_f32 v[86:87], v[132:133], v[86:87] op_sel:[1,0]
	v_pk_fma_f32 v[84:85], v[98:99], v[84:85], v[102:103]
	v_pk_fma_f32 v[86:87], v[96:97], v[86:87], v[100:101]
	v_cndmask_b32_e64 v93, v167, v145, s[4:5]
	v_cndmask_b32_e64 v92, v166, v144, s[4:5]
	v_pk_mul_f32 v[84:85], v[84:85], s[70:71] op_sel_hi:[1,0]
	v_cndmask_b32_e64 v91, v165, v143, s[4:5]
	v_cndmask_b32_e64 v90, v164, v142, s[4:5]
	v_pk_mul_f32 v[86:87], v[86:87], s[70:71] op_sel_hi:[1,0]
	v_pk_fma_f32 v[82:83], v[82:83], v[92:93], v[84:85]
	v_pk_fma_f32 v[80:81], v[80:81], v[90:91], v[86:87]
	v_cndmask_b32_e64 v85, v165, v143, s[6:7]
	v_cvt_pk_bf16_f32 v185, v80, v81
	v_cvt_pk_bf16_f32 v181, v82, v83
	v_sub_f32_e32 v83, v187, v130
	v_sub_f32_e32 v82, v186, v130
	v_sub_f32_e32 v81, v190, v130
	v_sub_f32_e32 v80, v188, v130
	v_pk_mul_f32 v[82:83], v[130:131], v[82:83] op_sel:[1,0]
	v_pk_mul_f32 v[80:81], v[130:131], v[80:81] op_sel:[1,0]
	v_pk_fma_f32 v[82:83], v[96:97], v[82:83], v[100:101]
	v_pk_fma_f32 v[80:81], v[98:99], v[80:81], v[102:103]
	v_cndmask_b32_e64 v84, v164, v142, s[6:7]
	v_pk_mul_f32 v[82:83], v[82:83], s[70:71] op_sel_hi:[1,0]
	v_cndmask_b32_e64 v87, v167, v145, s[6:7]
	v_cndmask_b32_e64 v86, v166, v144, s[6:7]
	v_pk_mul_f32 v[80:81], v[80:81], s[70:71] op_sel_hi:[1,0]
	v_pk_fma_f32 v[76:77], v[76:77], v[84:85], v[82:83]
	v_lshlrev_b32_e32 v192, 16, v170
	v_and_b32_e32 v170, 0xffff0000, v170
	v_pk_fma_f32 v[78:79], v[78:79], v[86:87], v[80:81]
	v_cvt_pk_bf16_f32 v198, v76, v77
	v_sub_f32_e32 v77, v194, v128
	v_sub_f32_e32 v76, v193, v128
	v_cvt_pk_bf16_f32 v191, v78, v79
	v_sub_f32_e32 v79, v170, v128
	v_sub_f32_e32 v78, v192, v128
	v_pk_mul_f32 v[76:77], v[128:129], v[76:77] op_sel:[1,0]
	v_pk_mul_f32 v[78:79], v[128:129], v[78:79] op_sel:[1,0]
	v_pk_fma_f32 v[76:77], v[98:99], v[76:77], v[102:103]
	v_pk_fma_f32 v[78:79], v[96:97], v[78:79], v[100:101]
	v_cndmask_b32_e64 v83, v167, v145, s[8:9]
	v_cndmask_b32_e64 v82, v166, v144, s[8:9]
	v_pk_mul_f32 v[76:77], v[76:77], s[70:71] op_sel_hi:[1,0]
	v_lshlrev_b32_e32 v195, 16, v176
	v_and_b32_e32 v176, 0xffff0000, v176
	v_cndmask_b32_e64 v81, v165, v143, s[8:9]
	v_cndmask_b32_e64 v80, v164, v142, s[8:9]
	v_pk_mul_f32 v[78:79], v[78:79], s[70:71] op_sel_hi:[1,0]
	v_pk_fma_f32 v[30:31], v[30:31], v[82:83], v[76:77]
	v_pk_fma_f32 v[28:29], v[28:29], v[80:81], v[78:79]
	v_lshlrev_b32_e32 v196, 16, v177
	v_cvt_pk_bf16_f32 v203, v28, v29
	v_cvt_pk_bf16_f32 v201, v30, v31
	v_sub_f32_e32 v31, v176, v0
	v_sub_f32_e32 v30, v195, v0
	v_and_b32_e32 v177, 0xffff0000, v177
	v_pk_mul_f32 v[30:31], v[0:1], v[30:31] op_sel:[1,0]
	v_sub_f32_e32 v29, v177, v0
	v_sub_f32_e32 v28, v196, v0
	v_pk_fma_f32 v[30:31], v[96:97], v[30:31], v[100:101]
	v_pk_mul_f32 v[28:29], v[0:1], v[28:29] op_sel:[1,0]
	v_cndmask_b32_e64 v77, v165, v143, s[10:11]
	v_cndmask_b32_e64 v76, v164, v142, s[10:11]
	v_pk_mul_f32 v[30:31], v[30:31], s[70:71] op_sel_hi:[1,0]
	v_pk_fma_f32 v[28:29], v[98:99], v[28:29], v[102:103]
	v_pk_fma_f32 v[24:25], v[24:25], v[76:77], v[30:31]
	v_cndmask_b32_e64 v79, v167, v145, s[10:11]
	v_cndmask_b32_e64 v78, v166, v144, s[10:11]
	v_pk_mul_f32 v[28:29], v[28:29], s[70:71] op_sel_hi:[1,0]
	v_cvt_pk_bf16_f32 v213, v24, v25
	v_add_u32_e32 v24, 0x80, v154
	v_pk_fma_f32 v[26:27], v[26:27], v[78:79], v[28:29]
	v_readlane_b32 s45, v255, 24
	v_cvt_pk_bf16_f32 v148, v26, v27
	v_readlane_b32 s50, v255, 29
	v_ashrrev_i32_e32 v25, 31, v24
	v_lshl_add_u64 v[26:27], v[24:25], 1, s[58:59]
	v_lshl_add_u64 v[28:29], v[26:27], 0, v[162:163]
	v_lshl_add_u64 v[30:31], v[26:27], 0, v[160:161]
	v_lshl_add_u64 v[76:77], v[26:27], 0, v[158:159]
	v_lshl_add_u64 v[78:79], v[26:27], 0, v[156:157]
	global_load_dwordx2 v[96:97], v[28:29], off
	global_load_dwordx2 v[98:99], v[30:31], off
	global_load_dwordx2 v[100:101], v[76:77], off
	global_load_dwordx2 v[102:103], v[78:79], off
	v_lshl_add_u64 v[28:29], v[26:27], 0, v[152:153]
	v_lshl_add_u64 v[26:27], v[26:27], 0, v[150:151]
	global_load_dwordx2 v[138:139], v[28:29], off
	global_load_dwordx2 v[142:143], v[26:27], off
	v_lshlrev_b64 v[28:29], 2, v[24:25]
	v_lshl_add_u64 v[30:31], s[30:31], 0, v[28:29]
	global_load_dwordx4 v[76:79], v[30:31], off
	v_lshl_add_u64 v[30:31], s[40:41], 0, v[28:29]
	v_lshl_add_u64 v[24:25], s[0:1], 0, v[28:29]
	v_lshl_add_u64 v[26:27], s[20:21], 0, v[28:29]
	global_load_dwordx4 v[80:83], v[30:31], off
	global_load_dwordx4 v[84:87], v[24:25], off
	global_load_dwordx4 v[90:93], v[26:27], off
	v_lshl_add_u64 v[24:25], s[46:47], 0, v[28:29]
	v_lshl_add_u64 v[28:29], s[48:49], 0, v[28:29]
	global_load_dwordx4 v[24:27], v[24:25], off
	v_readlane_b32 s51, v255, 30
	global_load_dwordx4 v[28:31], v[28:29], off
	s_waitcnt vmcnt(6)
	s_nop 0
	v_lshlrev_b32_e32 v89, 16, v96
	v_and_b32_e32 v94, 0xffff0000, v96
	v_lshlrev_b32_e32 v96, 16, v97
	v_and_b32_e32 v97, 0xffff0000, v97
	v_sub_f32_e32 v97, v97, v136
	v_sub_f32_e32 v96, v96, v136
	v_lshlrev_b32_e32 v104, 16, v98
	v_and_b32_e32 v106, 0xffff0000, v98
	v_lshlrev_b32_e32 v117, 16, v99
	v_and_b32_e32 v144, 0xffff0000, v99
	v_sub_f32_e32 v99, v94, v136
	v_sub_f32_e32 v98, v89, v136
	v_pk_mul_f32 v[96:97], v[136:137], v[96:97] op_sel:[1,0]
	v_pk_mul_f32 v[98:99], v[136:137], v[98:99] op_sel:[1,0]
	s_waitcnt vmcnt(4)
	v_pk_fma_f32 v[96:97], v[78:79], v[96:97], v[82:83]
	v_lshlrev_b32_e32 v167, 16, v102
	v_and_b32_e32 v168, 0xffff0000, v102
	v_lshlrev_b32_e32 v169, 16, v103
	v_and_b32_e32 v170, 0xffff0000, v103
	v_pk_fma_f32 v[98:99], v[76:77], v[98:99], v[80:81]
	s_waitcnt vmcnt(2)
	v_cndmask_b32_e64 v103, v93, v87, s[12:13]
	v_cndmask_b32_e64 v102, v92, v86, s[12:13]
	v_pk_mul_f32 v[96:97], v[96:97], s[70:71] op_sel_hi:[1,0]
	v_lshlrev_b32_e32 v145, 16, v100
	v_and_b32_e32 v164, 0xffff0000, v100
	v_lshlrev_b32_e32 v165, 16, v101
	v_and_b32_e32 v166, 0xffff0000, v101
	v_cndmask_b32_e64 v101, v91, v85, s[12:13]
	v_cndmask_b32_e64 v100, v90, v84, s[12:13]
	v_pk_mul_f32 v[98:99], v[98:99], s[70:71] op_sel_hi:[1,0]
	v_pk_fma_f32 v[74:75], v[74:75], v[102:103], v[96:97]
	v_pk_fma_f32 v[72:73], v[72:73], v[100:101], v[98:99]
	v_cndmask_b32_e32 v97, v91, v85, vcc
	v_cvt_pk_bf16_f32 v89, v72, v73
	v_cvt_pk_bf16_f32 v94, v74, v75
	v_sub_f32_e32 v75, v106, v134
	v_sub_f32_e32 v74, v104, v134
	v_sub_f32_e32 v73, v144, v134
	v_sub_f32_e32 v72, v117, v134
	v_pk_mul_f32 v[74:75], v[134:135], v[74:75] op_sel:[1,0]
	v_pk_mul_f32 v[72:73], v[134:135], v[72:73] op_sel:[1,0]
	v_pk_fma_f32 v[74:75], v[76:77], v[74:75], v[80:81]
	v_pk_fma_f32 v[72:73], v[78:79], v[72:73], v[82:83]
	v_cndmask_b32_e32 v96, v90, v84, vcc
	v_pk_mul_f32 v[74:75], v[74:75], s[70:71] op_sel_hi:[1,0]
	v_cndmask_b32_e32 v99, v93, v87, vcc
	v_cndmask_b32_e32 v98, v92, v86, vcc
	v_pk_mul_f32 v[72:73], v[72:73], s[70:71] op_sel_hi:[1,0]
	v_pk_fma_f32 v[68:69], v[68:69], v[96:97], v[74:75]
	v_pk_fma_f32 v[70:71], v[70:71], v[98:99], v[72:73]
	v_cvt_pk_bf16_f32 v177, v68, v69
	v_sub_f32_e32 v69, v166, v132
	v_sub_f32_e32 v68, v165, v132
	v_cvt_pk_bf16_f32 v176, v70, v71
	v_sub_f32_e32 v71, v164, v132
	v_sub_f32_e32 v70, v145, v132
	v_pk_mul_f32 v[68:69], v[132:133], v[68:69] op_sel:[1,0]
	v_pk_mul_f32 v[70:71], v[132:133], v[70:71] op_sel:[1,0]
	v_pk_fma_f32 v[68:69], v[78:79], v[68:69], v[82:83]
	v_pk_fma_f32 v[70:71], v[76:77], v[70:71], v[80:81]
	v_cndmask_b32_e64 v75, v93, v87, s[4:5]
	v_cndmask_b32_e64 v74, v92, v86, s[4:5]
	v_pk_mul_f32 v[68:69], v[68:69], s[70:71] op_sel_hi:[1,0]
	v_cndmask_b32_e64 v73, v91, v85, s[4:5]
	v_cndmask_b32_e64 v72, v90, v84, s[4:5]
	v_pk_mul_f32 v[70:71], v[70:71], s[70:71] op_sel_hi:[1,0]
	v_pk_fma_f32 v[66:67], v[66:67], v[74:75], v[68:69]
	v_pk_fma_f32 v[64:65], v[64:65], v[72:73], v[70:71]
	v_cndmask_b32_e64 v69, v91, v85, s[6:7]
	v_cvt_pk_bf16_f32 v188, v64, v65
	v_cvt_pk_bf16_f32 v187, v66, v67
	v_sub_f32_e32 v67, v168, v130
	v_sub_f32_e32 v66, v167, v130
	v_sub_f32_e32 v65, v170, v130
	v_sub_f32_e32 v64, v169, v130
	v_pk_mul_f32 v[66:67], v[130:131], v[66:67] op_sel:[1,0]
	v_pk_mul_f32 v[64:65], v[130:131], v[64:65] op_sel:[1,0]
	v_pk_fma_f32 v[66:67], v[76:77], v[66:67], v[80:81]
	v_pk_fma_f32 v[64:65], v[78:79], v[64:65], v[82:83]
	v_cndmask_b32_e64 v68, v90, v84, s[6:7]
	v_pk_mul_f32 v[66:67], v[66:67], s[70:71] op_sel_hi:[1,0]
	v_lshlrev_b32_e32 v174, 16, v139
	v_and_b32_e32 v139, 0xffff0000, v139
	v_cndmask_b32_e64 v71, v93, v87, s[6:7]
	v_cndmask_b32_e64 v70, v92, v86, s[6:7]
	v_pk_mul_f32 v[64:65], v[64:65], s[70:71] op_sel_hi:[1,0]
	v_pk_fma_f32 v[60:61], v[60:61], v[68:69], v[66:67]
	v_lshlrev_b32_e32 v172, 16, v138
	v_and_b32_e32 v138, 0xffff0000, v138
	v_pk_fma_f32 v[62:63], v[62:63], v[70:71], v[64:65]
	v_cvt_pk_bf16_f32 v195, v60, v61
	v_sub_f32_e32 v61, v139, v128
	v_sub_f32_e32 v60, v174, v128
	v_cvt_pk_bf16_f32 v194, v62, v63
	v_sub_f32_e32 v63, v138, v128
	v_sub_f32_e32 v62, v172, v128
	v_pk_mul_f32 v[60:61], v[128:129], v[60:61] op_sel:[1,0]
	v_pk_mul_f32 v[62:63], v[128:129], v[62:63] op_sel:[1,0]
	v_pk_fma_f32 v[60:61], v[78:79], v[60:61], v[82:83]
	v_pk_fma_f32 v[62:63], v[76:77], v[62:63], v[80:81]
	v_cndmask_b32_e64 v67, v93, v87, s[8:9]
	v_cndmask_b32_e64 v66, v92, v86, s[8:9]
	v_pk_mul_f32 v[60:61], v[60:61], s[70:71] op_sel_hi:[1,0]
	v_lshlrev_b32_e32 v179, 16, v142
	v_and_b32_e32 v142, 0xffff0000, v142
	v_cndmask_b32_e64 v65, v91, v85, s[8:9]
	v_cndmask_b32_e64 v64, v90, v84, s[8:9]
	v_pk_mul_f32 v[62:63], v[62:63], s[70:71] op_sel_hi:[1,0]
	v_pk_fma_f32 v[58:59], v[58:59], v[66:67], v[60:61]
	v_pk_fma_f32 v[56:57], v[56:57], v[64:65], v[62:63]
	v_lshlrev_b32_e32 v180, 16, v143
	v_cvt_pk_bf16_f32 v206, v56, v57
	v_cvt_pk_bf16_f32 v205, v58, v59
	v_sub_f32_e32 v59, v142, v0
	v_sub_f32_e32 v58, v179, v0
	v_and_b32_e32 v143, 0xffff0000, v143
	v_pk_mul_f32 v[58:59], v[0:1], v[58:59] op_sel:[1,0]
	v_sub_f32_e32 v57, v143, v0
	v_sub_f32_e32 v56, v180, v0
	v_pk_fma_f32 v[58:59], v[76:77], v[58:59], v[80:81]
	v_pk_mul_f32 v[56:57], v[0:1], v[56:57] op_sel:[1,0]
	v_cndmask_b32_e64 v61, v91, v85, s[10:11]
	v_cndmask_b32_e64 v60, v90, v84, s[10:11]
	v_pk_mul_f32 v[58:59], v[58:59], s[70:71] op_sel_hi:[1,0]
	v_pk_fma_f32 v[56:57], v[78:79], v[56:57], v[82:83]
	v_pk_fma_f32 v[52:53], v[52:53], v[60:61], v[58:59]
	v_cndmask_b32_e64 v63, v93, v87, s[10:11]
	v_cndmask_b32_e64 v62, v92, v86, s[10:11]
	v_pk_mul_f32 v[56:57], v[56:57], s[70:71] op_sel_hi:[1,0]
	v_cvt_pk_bf16_f32 v216, v52, v53
	v_add_u32_e32 v52, 0x84, v154
	v_pk_fma_f32 v[54:55], v[54:55], v[62:63], v[56:57]
	v_lshlrev_b32_e32 v76, 16, v88
	v_cvt_pk_bf16_f32 v215, v54, v55
	v_and_b32_e32 v77, 0xffff0000, v88
	v_ashrrev_i32_e32 v53, 31, v52
	v_lshl_add_u64 v[54:55], v[52:53], 1, s[58:59]
	v_lshl_add_u64 v[56:57], v[54:55], 0, v[162:163]
	v_lshl_add_u64 v[58:59], v[54:55], 0, v[160:161]
	v_lshl_add_u64 v[60:61], v[54:55], 0, v[158:159]
	v_lshl_add_u64 v[62:63], v[54:55], 0, v[156:157]
	global_load_dwordx2 v[80:81], v[56:57], off
	global_load_dwordx2 v[82:83], v[58:59], off
	global_load_dwordx2 v[138:139], v[60:61], off
	global_load_dwordx2 v[142:143], v[62:63], off
	v_lshl_add_u64 v[56:57], v[54:55], 0, v[152:153]
	v_lshl_add_u64 v[54:55], v[54:55], 0, v[150:151]
	global_load_dwordx2 v[144:145], v[56:57], off
	global_load_dwordx2 v[166:167], v[54:55], off
	v_lshlrev_b64 v[56:57], 2, v[52:53]
	v_lshl_add_u64 v[58:59], s[30:31], 0, v[56:57]
	global_load_dwordx4 v[68:71], v[58:59], off
	v_lshl_add_u64 v[58:59], s[40:41], 0, v[56:57]
	v_lshl_add_u64 v[52:53], s[0:1], 0, v[56:57]
	v_lshl_add_u64 v[54:55], s[20:21], 0, v[56:57]
	global_load_dwordx4 v[72:75], v[58:59], off
	global_load_dwordx4 v[60:63], v[52:53], off
	global_load_dwordx4 v[64:67], v[54:55], off
	v_lshl_add_u64 v[52:53], s[46:47], 0, v[56:57]
	v_lshlrev_b32_e32 v58, 2, v2
	global_load_dwordx4 v[52:55], v[52:53], off
	v_lshl_add_u64 v[56:57], s[48:49], 0, v[56:57]
	v_xor_b32_e32 v227, 64, v58
	v_xor_b32_e32 v226, 0x80, v58
	global_load_dwordx4 v[56:59], v[56:57], off
	v_mul_f32_e32 v84, v76, v76
	v_pk_fma_f32 v[92:93], v[76:77], v[76:77], v[84:85] op_sel_hi:[1,1,0]
	v_lshlrev_b32_e32 v86, 16, v89
	v_and_b32_e32 v87, 0xffff0000, v89
	v_lshlrev_b32_e32 v84, 16, v94
	v_and_b32_e32 v85, 0xffff0000, v94
	s_waitcnt vmcnt(13)
	v_pk_mul_f32 v[96:97], v[24:25], v[86:87]
	v_pk_mul_f32 v[168:169], v[26:27], v[84:85]
	s_waitcnt vmcnt(12)
	v_pk_mul_f32 v[196:197], v[28:29], v[96:97]
	v_pk_mul_f32 v[192:193], v[30:31], v[168:169]
	v_add_f32_e32 v79, v96, v97
	v_add_f32_e32 v92, v168, v169
	v_pk_mul_f32 v[90:91], v[24:25], v[96:97]
	v_add_f32_e32 v99, v79, v92
	v_mul_f32_e32 v98, v97, v97
	v_add_f32_e32 v79, v196, v197
	v_add_f32_e32 v97, v192, v193
	v_add_f32_e32 v97, v79, v97
	s_waitcnt vmcnt(6)
	s_nop 0
	v_lshlrev_b32_e32 v79, 16, v80
	v_and_b32_e32 v104, 0xffff0000, v80
	v_lshlrev_b32_e32 v80, 16, v81
	v_and_b32_e32 v81, 0xffff0000, v81
	v_lshlrev_b32_e32 v117, 16, v82
	v_and_b32_e32 v165, 0xffff0000, v82
	v_lshlrev_b32_e32 v170, 16, v83
	v_and_b32_e32 v172, 0xffff0000, v83
	v_sub_f32_e32 v83, v104, v136
	v_sub_f32_e32 v82, v79, v136
	v_sub_f32_e32 v81, v81, v136
	v_sub_f32_e32 v80, v80, v136
	v_pk_mul_f32 v[82:83], v[136:137], v[82:83] op_sel:[1,0]
	v_pk_mul_f32 v[80:81], v[136:137], v[80:81] op_sel:[1,0]
	s_waitcnt vmcnt(4)
	v_pk_fma_f32 v[82:83], v[68:69], v[82:83], v[72:73]
	v_pk_fma_f32 v[80:81], v[70:71], v[80:81], v[74:75]
	s_waitcnt vmcnt(2)
	v_cndmask_b32_e64 v137, v65, v61, s[12:13]
	v_cndmask_b32_e64 v136, v64, v60, s[12:13]
	v_pk_mul_f32 v[82:83], v[82:83], s[70:71] op_sel_hi:[1,0]
	v_lshlrev_b32_e32 v174, 16, v138
	v_and_b32_e32 v179, 0xffff0000, v138
	v_lshlrev_b32_e32 v180, 16, v139
	v_and_b32_e32 v184, 0xffff0000, v139
	v_cndmask_b32_e64 v139, v67, v63, s[12:13]
	v_cndmask_b32_e64 v138, v66, v62, s[12:13]
	v_pk_mul_f32 v[80:81], v[80:81], s[70:71] op_sel_hi:[1,0]
	v_pk_fma_f32 v[48:49], v[48:49], v[136:137], v[82:83]
	v_pk_fma_f32 v[50:51], v[50:51], v[138:139], v[80:81]
	v_cvt_pk_bf16_f32 v48, v48, v49
	v_lshlrev_b32_e32 v207, 16, v166
	v_cvt_pk_bf16_f32 v49, v50, v51
	v_lshlrev_b32_e32 v80, 16, v48
	v_and_b32_e32 v81, 0xffff0000, v48
	v_lshlrev_b32_e32 v82, 16, v49
	v_and_b32_e32 v83, 0xffff0000, v49
	v_and_b32_e32 v208, 0xffff0000, v166
	v_lshlrev_b32_e32 v209, 16, v167
	v_and_b32_e32 v210, 0xffff0000, v167
	s_waitcnt vmcnt(1)
	v_pk_mul_f32 v[136:137], v[52:53], v[80:81]
	v_pk_mul_f32 v[166:167], v[54:55], v[82:83]
	v_pk_mul_f32 v[88:89], v[26:27], v[168:169]
	v_mul_f32_e32 v92, v168, v168
	v_mul_f32_e32 v94, v169, v169
	s_waitcnt vmcnt(0)
	v_pk_mul_f32 v[168:169], v[58:59], v[166:167]
	v_add_f32_e32 v79, v136, v137
	v_add_f32_e32 v104, v166, v167
	v_pk_mul_f32 v[48:49], v[54:55], v[166:167]
	v_pk_mul_f32 v[50:51], v[52:53], v[136:137]
	v_pk_mul_f32 v[192:193], v[56:57], v[136:137]
	v_add_f32_e32 v139, v79, v104
	v_mul_f32_e32 v138, v137, v137
	v_mul_f32_e32 v104, v166, v166
	v_mul_f32_e32 v106, v167, v167
	v_add_f32_e32 v137, v168, v169
	v_sub_f32_e32 v167, v172, v134
	v_sub_f32_e32 v166, v170, v134
	v_sub_f32_e32 v169, v165, v134
	v_sub_f32_e32 v168, v117, v134
	v_pk_mul_f32 v[168:169], v[134:135], v[168:169] op_sel:[1,0]
	v_pk_mul_f32 v[134:135], v[134:135], v[166:167] op_sel:[1,0]
	v_pk_fma_f32 v[166:167], v[68:69], v[168:169], v[72:73]
	v_pk_fma_f32 v[134:135], v[70:71], v[134:135], v[74:75]
	v_add_f32_e32 v79, v192, v193
	v_cndmask_b32_e32 v169, v65, v61, vcc
	v_cndmask_b32_e32 v168, v64, v60, vcc
	v_cndmask_b32_e32 v193, v67, v63, vcc
	v_cndmask_b32_e32 v192, v66, v62, vcc
	v_pk_mul_f32 v[166:167], v[166:167], s[70:71] op_sel_hi:[1,0]
	v_pk_mul_f32 v[134:135], v[134:135], s[70:71] op_sel_hi:[1,0]
	v_pk_fma_f32 v[44:45], v[44:45], v[168:169], v[166:167]
	v_pk_fma_f32 v[46:47], v[46:47], v[192:193], v[134:135]
	v_cvt_pk_bf16_f32 v45, v44, v45
	v_sub_f32_e32 v135, v179, v132
	v_cvt_pk_bf16_f32 v44, v46, v47
	v_sub_f32_e32 v47, v184, v132
	v_sub_f32_e32 v46, v180, v132
	v_sub_f32_e32 v134, v174, v132
	v_pk_mul_f32 v[134:135], v[132:133], v[134:135] op_sel:[1,0]
	v_pk_mul_f32 v[46:47], v[132:133], v[46:47] op_sel:[1,0]
	v_pk_fma_f32 v[132:133], v[68:69], v[134:135], v[72:73]
	v_pk_fma_f32 v[46:47], v[70:71], v[46:47], v[74:75]
	v_cndmask_b32_e64 v135, v65, v61, s[4:5]
	v_cndmask_b32_e64 v134, v64, v60, s[4:5]
	v_cndmask_b32_e64 v167, v67, v63, s[4:5]
	v_cndmask_b32_e64 v166, v66, v62, s[4:5]
	v_pk_mul_f32 v[132:133], v[132:133], s[70:71] op_sel_hi:[1,0]
	v_pk_mul_f32 v[46:47], v[46:47], s[70:71] op_sel_hi:[1,0]
	v_lshlrev_b32_e32 v186, 16, v142
	v_and_b32_e32 v190, 0xffff0000, v142
	v_lshlrev_b32_e32 v196, 16, v143
	v_and_b32_e32 v197, 0xffff0000, v143
	v_pk_fma_f32 v[46:47], v[42:43], v[166:167], v[46:47]
	v_pk_fma_f32 v[40:41], v[40:41], v[134:135], v[132:133]
	v_cndmask_b32_e64 v133, v67, v63, s[6:7]
	v_cvt_pk_bf16_f32 v43, v40, v41
	v_cvt_pk_bf16_f32 v42, v46, v47
	v_sub_f32_e32 v41, v197, v130
	v_sub_f32_e32 v40, v196, v130
	v_sub_f32_e32 v47, v190, v130
	v_sub_f32_e32 v46, v186, v130
	v_pk_mul_f32 v[46:47], v[130:131], v[46:47] op_sel:[1,0]
	v_pk_mul_f32 v[40:41], v[130:131], v[40:41] op_sel:[1,0]
	v_pk_fma_f32 v[46:47], v[68:69], v[46:47], v[72:73]
	v_pk_fma_f32 v[40:41], v[70:71], v[40:41], v[74:75]
	v_cndmask_b32_e64 v131, v65, v61, s[6:7]
	v_cndmask_b32_e64 v130, v64, v60, s[6:7]
	v_cndmask_b32_e64 v132, v66, v62, s[6:7]
	v_pk_mul_f32 v[46:47], v[46:47], s[70:71] op_sel_hi:[1,0]
	v_pk_mul_f32 v[40:41], v[40:41], s[70:71] op_sel_hi:[1,0]
	v_lshlrev_b32_e32 v199, 16, v144
	v_and_b32_e32 v200, 0xffff0000, v144
	v_lshlrev_b32_e32 v202, 16, v145
	v_and_b32_e32 v204, 0xffff0000, v145
	v_pk_fma_f32 v[38:39], v[38:39], v[132:133], v[40:41]
	v_pk_fma_f32 v[36:37], v[36:37], v[130:131], v[46:47]
	v_cndmask_b32_e64 v47, v65, v61, s[8:9]
	v_cvt_pk_bf16_f32 v41, v36, v37
	v_cvt_pk_bf16_f32 v40, v38, v39
	v_sub_f32_e32 v37, v204, v128
	v_sub_f32_e32 v36, v202, v128
	v_sub_f32_e32 v39, v200, v128
	v_sub_f32_e32 v38, v199, v128
	v_pk_mul_f32 v[38:39], v[128:129], v[38:39] op_sel:[1,0]
	v_pk_mul_f32 v[36:37], v[128:129], v[36:37] op_sel:[1,0]
	v_pk_fma_f32 v[38:39], v[68:69], v[38:39], v[72:73]
	v_pk_fma_f32 v[36:37], v[70:71], v[36:37], v[74:75]
	v_cndmask_b32_e64 v46, v64, v60, s[8:9]
	v_cndmask_b32_e64 v129, v67, v63, s[8:9]
	v_cndmask_b32_e64 v128, v66, v62, s[8:9]
	v_pk_mul_f32 v[38:39], v[38:39], s[70:71] op_sel_hi:[1,0]
	v_pk_mul_f32 v[36:37], v[36:37], s[70:71] op_sel_hi:[1,0]
	v_pk_fma_f32 v[32:33], v[32:33], v[46:47], v[38:39]
	v_pk_fma_f32 v[34:35], v[34:35], v[128:129], v[36:37]
	v_cvt_pk_bf16_f32 v39, v32, v33
	v_sub_f32_e32 v33, v210, v0
	v_cvt_pk_bf16_f32 v38, v34, v35
	v_sub_f32_e32 v32, v209, v0
	v_sub_f32_e32 v35, v208, v0
	v_sub_f32_e32 v34, v207, v0
	v_pk_mul_f32 v[34:35], v[0:1], v[34:35] op_sel:[1,0]
	v_pk_mul_f32 v[0:1], v[0:1], v[32:33] op_sel:[1,0]
	v_and_b32_e32 v164, 0xffff0000, v107
	v_pk_fma_f32 v[0:1], v[70:71], v[0:1], v[74:75]
	v_lshlrev_b32_e32 v78, 16, v105
	v_pk_fma_f32 v[32:33], v[68:69], v[34:35], v[72:73]
	v_cndmask_b32_e64 v35, v67, v63, s[10:11]
	v_cndmask_b32_e64 v34, v66, v62, s[10:11]
	v_pk_mul_f32 v[0:1], v[0:1], s[70:71] op_sel_hi:[1,0]
	v_lshlrev_b32_e32 v166, 16, v107
	v_and_b32_e32 v169, 0xffff0000, v95
	v_and_b32_e32 v168, 0xffff0000, v105
	v_add_f32_e32 v137, v79, v137
	v_pk_fma_f32 v[62:63], v[22:23], v[34:35], v[0:1]
	v_lshlrev_b32_e32 v167, 16, v95
	v_mov_b32_e32 v79, v169
	v_mov_b32_e32 v0, v78
	v_mov_b32_e32 v1, v168
	v_mov_b32_e32 v22, v166
	v_mov_b32_e32 v23, v164
	v_mov_b32_e32 v165, v167
	v_pk_mul_f32 v[0:1], v[6:7], v[0:1]
	v_pk_mul_f32 v[22:23], v[4:5], v[22:23]
	v_pk_mul_f32 v[70:71], v[78:79], v[78:79]
	v_pk_mul_f32 v[66:67], v[166:167], v[166:167]
	v_pk_mul_f32 v[68:69], v[164:165], v[164:165]
	v_add_f32_e32 v71, v22, v23
	v_add_f32_e32 v74, v0, v1
	v_pk_mul_f32 v[72:73], v[168:169], v[168:169]
	v_add_f32_e32 v71, v71, v74
	v_pk_mov_b32 v[132:133], v[166:167], v[66:67] op_sel:[1,0]
	v_pk_mov_b32 v[68:69], v[168:169], v[68:69] op_sel:[1,0]
	v_add_f32_e32 v95, 0, v71
	v_pk_add_f32 v[68:69], v[132:133], v[68:69]
	v_mov_b32_e32 v132, v76
	v_mov_b32_e32 v133, v70
	v_pk_mov_b32 v[70:71], v[76:77], v[72:73] op_sel:[1,0]
	v_cndmask_b32_e64 v37, v65, v61, s[10:11]
	v_pk_add_f32 v[70:71], v[132:133], v[70:71]
	v_cndmask_b32_e64 v36, v64, v60, s[10:11]
	v_pk_mul_f32 v[34:35], v[4:5], v[22:23]
	v_pk_mul_f32 v[46:47], v[10:11], v[0:1]
	v_pk_mul_f32 v[64:65], v[8:9], v[22:23]
	v_mul_f32_e32 v74, v22, v22
	v_mul_f32_e32 v22, v1, v1
	v_pk_add_f32 v[68:69], v[68:69], v[70:71]
	v_pk_add_f32 v[70:71], v[166:167], v[164:165]
	v_pk_mul_f32 v[60:61], v[32:33], s[70:71] op_sel_hi:[1,0]
	v_pk_mul_f32 v[32:33], v[6:7], v[0:1]
	v_pk_fma_f32 v[130:131], v[0:1], v[0:1], v[22:23] op_sel_hi:[1,1,0]
	v_add_f32_e32 v0, v64, v65
	v_add_f32_e32 v1, v46, v47
	v_mov_b32_e32 v71, v67
	v_pk_add_f32 v[66:67], v[168:169], v[78:79]
	v_add_f32_e32 v0, v0, v1
	v_mov_b32_e32 v67, v73
	v_add_f32_e32 v105, 0, v0
	v_mov_b32_e32 v0, v167
	v_mov_b32_e32 v1, v169
	v_pk_add_f32 v[66:67], v[70:71], v[66:67]
	v_mov_b32_e32 v117, v93
	v_mul_f32_e32 v128, v23, v23
	v_pk_mul_f32 v[0:1], v[12:13], v[0:1]
	v_pk_mul_f32 v[22:23], v[14:15], v[76:77]
	v_pk_add_f32 v[66:67], v[66:67], v[116:117]
	v_pk_mul_f32 v[46:47], v[16:17], v[0:1]
	v_pk_add_f32 v[66:67], v[68:69], v[66:67]
	v_add_f32_e32 v68, v0, v1
	v_add_f32_e32 v69, v22, v23
	v_pk_mul_f32 v[64:65], v[18:19], v[22:23]
	v_add_f32_e32 v68, v68, v69
	v_add_f32_e32 v129, v32, v33
	v_pk_mul_f32 v[32:33], v[12:13], v[0:1]
	v_add_f32_e32 v69, v95, v68
	v_mul_f32_e32 v68, v0, v0
	v_mul_f32_e32 v70, v1, v1
	v_add_f32_e32 v0, v46, v47
	v_add_f32_e32 v1, v64, v65
	v_pk_mul_f32 v[102:103], v[86:87], v[86:87]
	v_pk_mul_f32 v[100:101], v[84:85], v[84:85]
	v_add_f32_e32 v0, v0, v1
	v_add_f32_e32 v75, v34, v35
	v_pk_mul_f32 v[34:35], v[14:15], v[22:23]
	v_mul_f32_e32 v72, v22, v22
	v_mul_f32_e32 v132, v23, v23
	v_add_f32_e32 v64, v105, v0
	v_mov_b32_e32 v0, v86
	v_mov_b32_e32 v1, v102
	v_mov_b32_e32 v102, v87
	v_mov_b32_e32 v22, v84
	v_mov_b32_e32 v23, v100
	v_mov_b32_e32 v100, v85
	v_pk_mul_f32 v[144:145], v[80:81], v[80:81]
	v_pk_mul_f32 v[142:143], v[82:83], v[82:83]
	v_pk_add_f32 v[0:1], v[0:1], v[102:103]
	v_pk_add_f32 v[22:23], v[22:23], v[100:101]
	v_mov_b32_e32 v46, v82
	v_pk_add_f32 v[0:1], v[0:1], v[22:23]
	v_mov_b32_e32 v22, v80
	v_mov_b32_e32 v23, v144
	v_mov_b32_e32 v144, v81
	v_mov_b32_e32 v47, v142
	v_mov_b32_e32 v142, v83
	v_pk_add_f32 v[22:23], v[22:23], v[144:145]
	v_pk_add_f32 v[46:47], v[46:47], v[142:143]
	v_mul_f32_e32 v136, v136, v136
	v_pk_add_f32 v[22:23], v[22:23], v[46:47]
	v_add_f32_e32 v46, v69, v99
	v_add_f32_e32 v47, v64, v97
	v_pk_add_f32 v[0:1], v[66:67], v[0:1]
	v_add_f32_e32 v66, v46, v139
	v_add_f32_e32 v67, v47, v137
	v_mov_b32_e32 v137, v50
	v_mov_b32_e32 v139, v51
	v_mov_b32_e32 v105, v48
	v_mov_b32_e32 v107, v49
	v_pk_add_f32 v[50:51], v[136:137], v[138:139]
	v_pk_add_f32 v[48:49], v[104:105], v[106:107]
	v_mov_b32_e32 v69, v32
	v_mov_b32_e32 v71, v33
	v_mov_b32_e32 v73, v34
	v_mov_b32_e32 v133, v35
	v_mul_f32_e32 v96, v96, v96
	v_mov_b32_e32 v97, v90
	v_mov_b32_e32 v99, v91
	v_mov_b32_e32 v93, v88
	v_mov_b32_e32 v95, v89
	v_pk_add_f32 v[48:49], v[50:51], v[48:49]
	v_pk_add_f32 v[50:51], v[74:75], v[128:129]
	v_mov_b32_e32 v131, v116
	v_pk_add_f32 v[32:33], v[68:69], v[70:71]
	v_pk_add_f32 v[34:35], v[72:73], v[132:133]
	v_pk_add_f32 v[46:47], v[96:97], v[98:99]
	v_pk_add_f32 v[64:65], v[92:93], v[94:95]
	v_pk_add_f32 v[50:51], v[50:51], v[130:131]
	v_pk_add_f32 v[32:33], v[32:33], v[34:35]
	v_pk_add_f32 v[46:47], v[46:47], v[64:65]
	v_pk_add_f32 v[32:33], v[50:51], v[32:33]
	v_pk_add_f32 v[0:1], v[0:1], v[22:23]
	v_pk_add_f32 v[32:33], v[32:33], v[46:47]
	ds_bpermute_b32 v22, v227, v0
	v_pk_add_f32 v[32:33], v[32:33], v[48:49]
	ds_bpermute_b32 v23, v227, v1
	ds_bpermute_b32 v79, v227, v66
	ds_bpermute_b32 v34, v227, v32
	ds_bpermute_b32 v35, v227, v33
	ds_bpermute_b32 v48, v227, v67
	s_waitcnt lgkmcnt(4)
	v_pk_add_f32 v[0:1], v[0:1], v[22:23]
	s_waitcnt lgkmcnt(3)
	v_add_f32_e32 v46, v66, v79
	ds_bpermute_b32 v22, v226, v0
	s_waitcnt lgkmcnt(2)
	v_pk_add_f32 v[32:33], v[32:33], v[34:35]
	s_waitcnt lgkmcnt(1)
	v_add_f32_e32 v48, v67, v48
	ds_bpermute_b32 v23, v226, v1
	ds_bpermute_b32 v47, v226, v46
	ds_bpermute_b32 v34, v226, v32
	ds_bpermute_b32 v35, v226, v33
	ds_bpermute_b32 v49, v226, v48
	v_cmp_gt_u32_e32 vcc, 16, v2
	v_readlane_b32 s52, v255, 31
	v_readlane_b32 s53, v255, 32
	v_readlane_b32 s54, v255, 33
	v_readlane_b32 s55, v255, 34
	v_pk_fma_f32 v[20:21], v[20:21], v[36:37], v[60:61]
	s_nop 0
	v_cvt_pk_bf16_f32 v37, v20, v21
	v_cvt_pk_bf16_f32 v36, v62, v63
	s_and_saveexec_b64 s[0:1], vcc
	s_cbranch_execz .LBB0_2453
	s_add_i32 s4, s81, 0
	s_waitcnt lgkmcnt(0)
	v_add_f32_e32 v50, v48, v49
	v_pk_add_f32 v[48:49], v[32:33], v[34:35]
	v_pk_add_f32 v[32:33], v[0:1], v[22:23]
	v_lshl_add_u32 v0, v127, 7, s4
	v_add_f32_e32 v34, v46, v47
	v_add_u32_e32 v0, 0x20000, v0
	v_mov_b32_e32 v35, v116
	v_mov_b32_e32 v51, v116
	ds_write_b128 v0, v[32:35]
	ds_write_b128 v0, v[48:51] offset:16

.LBB0_2987:
	s_mov_b32 s0, 0
	s_mov_b32 s1, 0
	s_mov_b32 s4, 0
	s_mov_b32 s5, 0
	s_mov_b32 s15, s85
	s_mov_b32 s87, s34
	v_mbcnt_lo_u32_b32 v2, -1, 0
	v_mbcnt_hi_u32_b32 v2, -1, v2
	s_mul_i32 s14, s15, 48
	v_and_or_b32 v127, v2, 15, s14
	s_mul_i32 s71, s96, 0xc0
	s_lshl_b32 s97, s87, 5
	v_ashrrev_i32_e32 v0, 1, v2
	s_lshl_b32 s0, s70, 8
	v_add_u32_e32 v160, s71, v127
	v_and_b32_e32 v0, -8, v0
	s_add_i32 s90, s97, s0
	v_add_u32_e32 v134, s90, v0
	v_lshlrev_b32_e32 v0, 1, v160
	v_ashrrev_i32_e32 v1, 31, v0
	v_lshl_add_u64 v[4:5], v[0:1], 2, s[82:83]
	v_add_u32_e32 v6, 32, v0
	v_add_u32_e32 v0, 64, v0
	v_add_u32_e32 v144, 0x60, v160
	v_ashrrev_i32_e32 v1, 31, v0
	v_lshlrev_b32_e32 v8, 1, v144
	v_mov_b32_e32 v128, 2.0
	v_mov_b32_e32 v126, 0x3a800000
	v_ashrrev_i32_e32 v7, 31, v6
	v_lshl_add_u64 v[0:1], v[0:1], 2, s[82:83]
	v_ashrrev_i32_e32 v9, 31, v8
	s_add_i32 s0, s71, 0xfffff000
	s_add_i32 s1, s71, 0xfffff0bf
	v_lshl_add_u64 v[6:7], v[6:7], 2, s[82:83]
	v_lshl_add_u64 v[10:11], v[8:9], 2, s[82:83]
	global_load_dwordx2 v[158:159], v[4:5], off
	global_load_dwordx2 v[152:153], v[6:7], off
	global_load_dwordx2 v[150:151], v[0:1], off
	global_load_dwordx2 v[148:149], v[10:11], off
	v_add_u32_e32 v0, 32, v8
	v_add_u32_e32 v4, 64, v8
	s_lshr_b32 s0, s0, 12
	s_lshr_b32 s1, s1, 12
	v_ashrrev_i32_e32 v1, 31, v0
	v_ashrrev_i32_e32 v5, 31, v4
	s_add_i32 s0, s0, 1
	s_add_i32 s1, s1, 1
	v_lshl_add_u64 v[0:1], v[0:1], 2, s[82:83]
	v_lshl_add_u64 v[4:5], v[4:5], 2, s[82:83]
	s_cmp_gt_i32 s96, 20
	global_load_dwordx2 v[146:147], v[0:1], off
	s_nop 0
	global_load_dwordx2 v[0:1], v[4:5], off
	v_mov_b32_e32 v4, v134
	s_cselect_b32 s1, s1, 0
	v_ashrrev_i32_e32 v161, 31, v160
	v_ashrrev_i32_e32 v5, 31, v4
	v_add_u32_e32 v162, 16, v160
	v_add_u32_e32 v164, 32, v160
	v_ashrrev_i32_e32 v145, 31, v144
	s_lshl_b32 s4, s1, 12
	v_lshl_add_u64 v[6:7], v[4:5], 1, s[58:59]
	v_lshlrev_b64 v[142:143], 11, v[160:161]
	v_ashrrev_i32_e32 v163, 31, v162
	v_ashrrev_i32_e32 v165, 31, v164
	v_lshlrev_b64 v[136:137], 11, v[144:145]
	v_add_u32_e32 v156, 0x70, v160
	s_cmp_gt_i32 s96, 21
	v_lshl_add_u64 v[8:9], v[6:7], 0, v[142:143]
	v_lshlrev_b64 v[140:141], 11, v[162:163]
	v_lshlrev_b64 v[138:139], 11, v[164:165]
	v_lshl_add_u64 v[132:133], v[6:7], 0, v[136:137]
	v_ashrrev_i32_e32 v157, 31, v156
	v_add_u32_e32 v154, 0x80, v160
	s_cselect_b32 s0, s0, 0
	v_lshl_add_u64 v[10:11], v[6:7], 0, v[140:141]
	v_lshl_add_u64 v[130:131], v[6:7], 0, v[138:139]
	global_load_dwordx2 v[170:171], v[8:9], off
	global_load_dword v166, v[8:9], off offset:256
	global_load_dwordx2 v[172:173], v[10:11], off
	global_load_dword v166, v[10:11], off offset:256
	global_load_dwordx2 v[174:175], v[130:131], off
	global_load_dword v166, v[130:131], off offset:256
	global_load_dwordx2 v[180:181], v[132:133], off
	global_load_dword v166, v[132:133], off offset:256
	v_lshlrev_b64 v[132:133], 11, v[156:157]
	v_ashrrev_i32_e32 v155, 31, v154
	s_cmp_lg_u32 s1, s0
	s_mul_i32 s38, s0, 0x1800
	v_lshl_add_u64 v[8:9], v[6:7], 0, v[132:133]
	v_lshlrev_b64 v[130:131], 11, v[154:155]
	s_cselect_b32 s65, s4, 0x7fffffff
	s_lshl_b64 s[74:75], s[38:39], 2
	v_readlane_b32 s6, v254, 19
	v_readlane_b32 s40, v255, 19
	v_lshl_add_u64 v[6:7], v[6:7], 0, v[130:131]
	global_load_dwordx2 v[182:183], v[8:9], off
	global_load_dword v166, v[8:9], off offset:256
	global_load_dwordx2 v[184:185], v[6:7], off
	global_load_dword v166, v[6:7], off offset:256
	s_mul_i32 s4, s1, 0x1800
	s_mov_b32 s5, s39
	v_lshlrev_b64 v[8:9], 2, v[4:5]
	s_add_u32 s0, s6, s74
	v_readlane_b32 s46, v255, 25
	v_readlane_b32 s47, v255, 26
	s_addc_u32 s1, s86, s75
	s_lshl_b64 s[72:73], s[4:5], 2
	v_readlane_b32 s48, v255, 27
	v_readlane_b32 s49, v255, 28
	v_lshl_add_u64 v[6:7], s[46:47], 0, v[8:9]
	s_add_u32 s76, s6, s72
	global_load_dwordx4 v[166:169], v[6:7], off
	v_lshl_add_u64 v[6:7], s[48:49], 0, v[8:9]
	v_lshl_add_u64 v[4:5], s[0:1], 0, v[8:9]
	s_addc_u32 s77, s86, s73
	global_load_dwordx4 v[176:179], v[6:7], off
	v_lshl_add_u64 v[6:7], s[76:77], 0, v[8:9]
	global_load_dwordx4 v[186:189], v[4:5], off
	global_load_dwordx4 v[194:197], v[6:7], off
	v_readlane_b32 s16, v254, 3
	v_readlane_b32 s17, v254, 4
	v_readlane_b32 s18, v254, 5
	v_readlane_b32 s19, v254, 6
	v_lshl_add_u64 v[4:5], s[16:17], 0, v[8:9]
	global_load_dwordx4 v[4:7], v[4:5], off
	v_lshl_add_u64 v[8:9], s[18:19], 0, v[8:9]
	global_load_dwordx4 v[8:11], v[8:9], off
	s_waitcnt vmcnt(0)
	s_nop 0
	v_lshlrev_b32_e32 v117, 16, v170
	v_and_b32_e32 v129, 0xffff0000, v170
	v_lshlrev_b32_e32 v135, 16, v171
	v_and_b32_e32 v145, 0xffff0000, v171
	v_lshlrev_b32_e32 v155, 16, v172
	v_and_b32_e32 v157, 0xffff0000, v172
	v_lshlrev_b32_e32 v163, 16, v173
	v_and_b32_e32 v165, 0xffff0000, v173
	v_sub_f32_e32 v171, v145, v158
	v_sub_f32_e32 v170, v135, v158
	v_sub_f32_e32 v173, v129, v158
	v_sub_f32_e32 v172, v117, v158
	v_pk_mul_f32 v[172:173], v[158:159], v[172:173] op_sel:[1,0]
	v_pk_mul_f32 v[170:171], v[158:159], v[170:171] op_sel:[1,0]
	v_cmp_gt_i32_e64 s[12:13], s65, v160
	v_lshlrev_b32_e32 v190, 16, v174
	v_pk_fma_f32 v[170:171], v[168:169], v[170:171], v[178:179]
	v_pk_fma_f32 v[172:173], v[166:167], v[172:173], v[176:177]
	v_and_b32_e32 v191, 0xffff0000, v174
	v_lshlrev_b32_e32 v192, 16, v175
	v_and_b32_e32 v193, 0xffff0000, v175
	v_cndmask_b32_e64 v161, v195, v187, s[12:13]
	v_cndmask_b32_e64 v160, v194, v186, s[12:13]
	v_cndmask_b32_e64 v175, v197, v189, s[12:13]
	v_cndmask_b32_e64 v174, v196, v188, s[12:13]
	v_pk_mul_f32 v[172:173], v[172:173], s[84:85] op_sel_hi:[1,0]
	v_pk_mul_f32 v[170:171], v[170:171], s[84:85] op_sel_hi:[1,0]
	v_pk_fma_f32 v[104:105], v[104:105], v[160:161], v[172:173]
	v_pk_fma_f32 v[170:171], v[106:107], v[174:175], v[170:171]
	v_cvt_pk_bf16_f32 v107, v104, v105
	v_sub_f32_e32 v161, v165, v152
	v_cvt_pk_bf16_f32 v105, v170, v171
	v_sub_f32_e32 v171, v157, v152
	v_sub_f32_e32 v170, v155, v152
	v_sub_f32_e32 v160, v163, v152
	v_pk_mul_f32 v[170:171], v[152:153], v[170:171] op_sel:[1,0]
	v_pk_mul_f32 v[160:161], v[152:153], v[160:161] op_sel:[1,0]
	v_pk_fma_f32 v[170:171], v[166:167], v[170:171], v[176:177]
	v_cmp_gt_i32_e32 vcc, s65, v162
	v_pk_fma_f32 v[160:161], v[168:169], v[160:161], v[178:179]
	v_pk_mul_f32 v[170:171], v[170:171], s[84:85] op_sel_hi:[1,0]
	v_cndmask_b32_e32 v163, v195, v187, vcc
	v_cndmask_b32_e32 v162, v194, v186, vcc
	v_cndmask_b32_e32 v173, v197, v189, vcc
	v_cndmask_b32_e32 v172, v196, v188, vcc
	v_pk_mul_f32 v[160:161], v[160:161], s[84:85] op_sel_hi:[1,0]
	v_pk_fma_f32 v[100:101], v[100:101], v[162:163], v[170:171]
	v_pk_fma_f32 v[102:103], v[102:103], v[172:173], v[160:161]
	v_cvt_pk_bf16_f32 v173, v100, v101
	v_sub_f32_e32 v101, v193, v150
	v_sub_f32_e32 v100, v192, v150
	v_cvt_pk_bf16_f32 v175, v102, v103
	v_sub_f32_e32 v103, v191, v150
	v_sub_f32_e32 v102, v190, v150
	v_pk_mul_f32 v[100:101], v[150:151], v[100:101] op_sel:[1,0]
	v_pk_mul_f32 v[102:103], v[150:151], v[102:103] op_sel:[1,0]
	v_pk_fma_f32 v[100:101], v[168:169], v[100:101], v[178:179]
	v_cmp_gt_i32_e64 s[4:5], s65, v164
	v_pk_fma_f32 v[102:103], v[166:167], v[102:103], v[176:177]
	v_pk_mul_f32 v[100:101], v[100:101], s[84:85] op_sel_hi:[1,0]
	v_cndmask_b32_e64 v163, v197, v189, s[4:5]
	v_cndmask_b32_e64 v162, v196, v188, s[4:5]
	v_lshlrev_b32_e32 v198, 16, v180
	v_and_b32_e32 v180, 0xffff0000, v180
	v_cndmask_b32_e64 v161, v195, v187, s[4:5]
	v_cndmask_b32_e64 v160, v194, v186, s[4:5]
	v_pk_mul_f32 v[102:103], v[102:103], s[84:85] op_sel_hi:[1,0]
	v_pk_fma_f32 v[98:99], v[98:99], v[162:163], v[100:101]
	v_lshlrev_b32_e32 v199, 16, v181
	v_and_b32_e32 v181, 0xffff0000, v181
	v_lshlrev_b32_e32 v201, 16, v183
	v_and_b32_e32 v202, 0xffff0000, v183
	v_lshlrev_b32_e32 v204, 16, v185
	v_and_b32_e32 v205, 0xffff0000, v185
	v_pk_fma_f32 v[96:97], v[96:97], v[160:161], v[102:103]
	v_cmp_gt_i32_e64 s[6:7], s65, v144
	v_cvt_pk_bf16_f32 v183, v96, v97
	v_cvt_pk_bf16_f32 v185, v98, v99
	v_sub_f32_e32 v99, v180, v148
	v_sub_f32_e32 v98, v198, v148
	v_sub_f32_e32 v97, v181, v148
	v_sub_f32_e32 v96, v199, v148
	v_pk_mul_f32 v[98:99], v[148:149], v[98:99] op_sel:[1,0]
	v_pk_mul_f32 v[96:97], v[148:149], v[96:97] op_sel:[1,0]
	v_pk_fma_f32 v[98:99], v[166:167], v[98:99], v[176:177]
	v_pk_fma_f32 v[96:97], v[168:169], v[96:97], v[178:179]
	v_cndmask_b32_e64 v101, v195, v187, s[6:7]
	v_cndmask_b32_e64 v100, v194, v186, s[6:7]
	v_pk_mul_f32 v[98:99], v[98:99], s[84:85] op_sel_hi:[1,0]
	v_cndmask_b32_e64 v103, v197, v189, s[6:7]
	v_cndmask_b32_e64 v102, v196, v188, s[6:7]
	v_pk_mul_f32 v[96:97], v[96:97], s[84:85] op_sel_hi:[1,0]
	v_pk_fma_f32 v[92:93], v[92:93], v[100:101], v[98:99]
	v_lshlrev_b32_e32 v200, 16, v182
	v_and_b32_e32 v182, 0xffff0000, v182
	v_pk_fma_f32 v[94:95], v[94:95], v[102:103], v[96:97]
	v_cvt_pk_bf16_f32 v193, v92, v93
	v_sub_f32_e32 v93, v202, v146
	v_sub_f32_e32 v92, v201, v146
	v_cvt_pk_bf16_f32 v165, v94, v95
	v_sub_f32_e32 v95, v182, v146
	v_sub_f32_e32 v94, v200, v146
	v_pk_mul_f32 v[92:93], v[146:147], v[92:93] op_sel:[1,0]
	v_pk_mul_f32 v[94:95], v[146:147], v[94:95] op_sel:[1,0]
	v_pk_fma_f32 v[92:93], v[168:169], v[92:93], v[178:179]
	v_cmp_gt_i32_e64 s[8:9], s65, v156
	v_pk_fma_f32 v[94:95], v[166:167], v[94:95], v[176:177]
	v_pk_mul_f32 v[92:93], v[92:93], s[84:85] op_sel_hi:[1,0]
	v_cndmask_b32_e64 v99, v197, v189, s[8:9]
	v_cndmask_b32_e64 v98, v196, v188, s[8:9]
	v_lshlrev_b32_e32 v203, 16, v184
	v_and_b32_e32 v184, 0xffff0000, v184
	v_cndmask_b32_e64 v97, v195, v187, s[8:9]
	v_cndmask_b32_e64 v96, v194, v186, s[8:9]
	v_pk_mul_f32 v[94:95], v[94:95], s[84:85] op_sel_hi:[1,0]
	v_pk_fma_f32 v[18:19], v[18:19], v[98:99], v[92:93]
	v_pk_fma_f32 v[16:17], v[16:17], v[96:97], v[94:95]
	v_cmp_gt_i32_e64 s[10:11], s65, v154
	v_cvt_pk_bf16_f32 v163, v16, v17
	v_cvt_pk_bf16_f32 v162, v18, v19
	v_sub_f32_e32 v19, v184, v0
	v_sub_f32_e32 v18, v203, v0
	v_pk_mul_f32 v[18:19], v[0:1], v[18:19] op_sel:[1,0]
	v_sub_f32_e32 v17, v205, v0
	v_sub_f32_e32 v16, v204, v0
	v_pk_fma_f32 v[18:19], v[166:167], v[18:19], v[176:177]
	v_pk_mul_f32 v[16:17], v[0:1], v[16:17] op_sel:[1,0]
	v_cndmask_b32_e64 v93, v195, v187, s[10:11]
	v_cndmask_b32_e64 v92, v194, v186, s[10:11]
	v_pk_mul_f32 v[18:19], v[18:19], s[84:85] op_sel_hi:[1,0]
	v_pk_fma_f32 v[16:17], v[168:169], v[16:17], v[178:179]
	v_pk_fma_f32 v[12:13], v[12:13], v[92:93], v[18:19]
	v_cndmask_b32_e64 v95, v197, v189, s[10:11]
	v_cndmask_b32_e64 v94, v196, v188, s[10:11]
	v_pk_mul_f32 v[16:17], v[16:17], s[84:85] op_sel_hi:[1,0]
	v_cvt_pk_bf16_f32 v135, v12, v13
	v_or_b32_e32 v12, 4, v134
	v_pk_fma_f32 v[14:15], v[14:15], v[94:95], v[16:17]
	v_readlane_b32 s41, v255, 20
	v_cvt_pk_bf16_f32 v129, v14, v15
	v_readlane_b32 s42, v255, 21
	v_ashrrev_i32_e32 v13, 31, v12
	v_lshl_add_u64 v[14:15], v[12:13], 1, s[58:59]
	v_lshl_add_u64 v[16:17], v[14:15], 0, v[142:143]
	v_lshl_add_u64 v[18:19], v[14:15], 0, v[140:141]
	v_lshl_add_u64 v[92:93], v[14:15], 0, v[138:139]
	v_lshl_add_u64 v[94:95], v[14:15], 0, v[136:137]
	global_load_dwordx2 v[144:145], v[16:17], off
	global_load_dwordx2 v[160:161], v[18:19], off
	global_load_dwordx2 v[166:167], v[92:93], off
	global_load_dwordx2 v[168:169], v[94:95], off
	v_lshl_add_u64 v[16:17], v[14:15], 0, v[132:133]
	v_lshl_add_u64 v[14:15], v[14:15], 0, v[130:131]
	global_load_dwordx2 v[170:171], v[16:17], off
	global_load_dwordx2 v[176:177], v[14:15], off
	v_lshlrev_b64 v[16:17], 2, v[12:13]
	v_lshl_add_u64 v[18:19], s[46:47], 0, v[16:17]
	global_load_dwordx4 v[92:95], v[18:19], off
	v_lshl_add_u64 v[18:19], s[48:49], 0, v[16:17]
	v_lshl_add_u64 v[12:13], s[0:1], 0, v[16:17]
	v_lshl_add_u64 v[14:15], s[76:77], 0, v[16:17]
	global_load_dwordx4 v[96:99], v[18:19], off
	global_load_dwordx4 v[100:103], v[12:13], off
	global_load_dwordx4 v[154:157], v[14:15], off
	v_lshl_add_u64 v[12:13], s[16:17], 0, v[16:17]
	v_lshl_add_u64 v[16:17], s[18:19], 0, v[16:17]
	global_load_dwordx4 v[12:15], v[12:13], off
	v_readlane_b32 s43, v255, 22
	global_load_dwordx4 v[16:19], v[16:17], off
	s_waitcnt vmcnt(6)
	s_nop 0
	v_lshlrev_b32_e32 v104, 16, v144
	v_and_b32_e32 v106, 0xffff0000, v144
	v_lshlrev_b32_e32 v117, 16, v145
	v_and_b32_e32 v144, 0xffff0000, v145
	v_lshlrev_b32_e32 v164, 16, v160
	v_and_b32_e32 v172, 0xffff0000, v160
	v_lshlrev_b32_e32 v174, 16, v161
	v_and_b32_e32 v178, 0xffff0000, v161
	v_sub_f32_e32 v145, v144, v158
	v_sub_f32_e32 v144, v117, v158
	v_sub_f32_e32 v161, v106, v158
	v_sub_f32_e32 v160, v104, v158
	v_pk_mul_f32 v[160:161], v[158:159], v[160:161] op_sel:[1,0]
	v_pk_mul_f32 v[144:145], v[158:159], v[144:145] op_sel:[1,0]
	s_waitcnt vmcnt(4)
	v_pk_fma_f32 v[160:161], v[92:93], v[160:161], v[96:97]
	v_pk_fma_f32 v[144:145], v[94:95], v[144:145], v[98:99]
	v_lshlrev_b32_e32 v179, 16, v166
	v_and_b32_e32 v180, 0xffff0000, v166
	v_lshlrev_b32_e32 v181, 16, v167
	v_and_b32_e32 v182, 0xffff0000, v167
	v_lshlrev_b32_e32 v184, 16, v168
	v_and_b32_e32 v186, 0xffff0000, v168
	v_lshlrev_b32_e32 v187, 16, v169
	v_and_b32_e32 v189, 0xffff0000, v169
	s_waitcnt vmcnt(2)
	v_cndmask_b32_e64 v167, v155, v101, s[12:13]
	v_cndmask_b32_e64 v166, v154, v100, s[12:13]
	v_cndmask_b32_e64 v169, v157, v103, s[12:13]
	v_cndmask_b32_e64 v168, v156, v102, s[12:13]
	v_pk_mul_f32 v[160:161], v[160:161], s[84:85] op_sel_hi:[1,0]
	v_pk_mul_f32 v[144:145], v[144:145], s[84:85] op_sel_hi:[1,0]
	v_pk_fma_f32 v[88:89], v[88:89], v[166:167], v[160:161]
	v_pk_fma_f32 v[144:145], v[90:91], v[168:169], v[144:145]
	v_sub_f32_e32 v161, v172, v152
	v_sub_f32_e32 v160, v164, v152
	v_cvt_pk_bf16_f32 v91, v88, v89
	v_cvt_pk_bf16_f32 v88, v144, v145
	v_sub_f32_e32 v145, v178, v152
	v_sub_f32_e32 v144, v174, v152
	v_pk_mul_f32 v[160:161], v[152:153], v[160:161] op_sel:[1,0]
	v_pk_mul_f32 v[144:145], v[152:153], v[144:145] op_sel:[1,0]
	v_pk_fma_f32 v[160:161], v[92:93], v[160:161], v[96:97]
	v_pk_fma_f32 v[144:145], v[94:95], v[144:145], v[98:99]
	v_cndmask_b32_e32 v167, v155, v101, vcc
	v_cndmask_b32_e32 v166, v154, v100, vcc
	v_pk_mul_f32 v[160:161], v[160:161], s[84:85] op_sel_hi:[1,0]
	v_cndmask_b32_e32 v169, v157, v103, vcc
	v_cndmask_b32_e32 v168, v156, v102, vcc
	v_pk_mul_f32 v[144:145], v[144:145], s[84:85] op_sel_hi:[1,0]
	v_pk_fma_f32 v[84:85], v[84:85], v[166:167], v[160:161]
	v_pk_fma_f32 v[86:87], v[86:87], v[168:169], v[144:145]
	v_cvt_pk_bf16_f32 v178, v84, v85
	v_sub_f32_e32 v85, v182, v150
	v_sub_f32_e32 v84, v181, v150
	v_cvt_pk_bf16_f32 v167, v86, v87
	v_sub_f32_e32 v87, v180, v150
	v_sub_f32_e32 v86, v179, v150
	v_pk_mul_f32 v[84:85], v[150:151], v[84:85] op_sel:[1,0]
	v_pk_mul_f32 v[86:87], v[150:151], v[86:87] op_sel:[1,0]
	v_pk_fma_f32 v[84:85], v[94:95], v[84:85], v[98:99]
	v_pk_fma_f32 v[86:87], v[92:93], v[86:87], v[96:97]
	v_cndmask_b32_e64 v161, v157, v103, s[4:5]
	v_cndmask_b32_e64 v160, v156, v102, s[4:5]
	v_pk_mul_f32 v[84:85], v[84:85], s[84:85] op_sel_hi:[1,0]
	v_cndmask_b32_e64 v145, v155, v101, s[4:5]
	v_cndmask_b32_e64 v144, v154, v100, s[4:5]
	v_pk_mul_f32 v[86:87], v[86:87], s[84:85] op_sel_hi:[1,0]
	v_pk_fma_f32 v[82:83], v[82:83], v[160:161], v[84:85]
	v_pk_fma_f32 v[80:81], v[80:81], v[144:145], v[86:87]
	v_cndmask_b32_e64 v85, v155, v101, s[6:7]
	v_cvt_pk_bf16_f32 v188, v80, v81
	v_cvt_pk_bf16_f32 v181, v82, v83
	v_sub_f32_e32 v83, v186, v148
	v_sub_f32_e32 v82, v184, v148
	v_sub_f32_e32 v81, v189, v148
	v_sub_f32_e32 v80, v187, v148
	v_pk_mul_f32 v[82:83], v[148:149], v[82:83] op_sel:[1,0]
	v_pk_mul_f32 v[80:81], v[148:149], v[80:81] op_sel:[1,0]
	v_pk_fma_f32 v[82:83], v[92:93], v[82:83], v[96:97]
	v_pk_fma_f32 v[80:81], v[94:95], v[80:81], v[98:99]
	v_cndmask_b32_e64 v84, v154, v100, s[6:7]
	v_pk_mul_f32 v[82:83], v[82:83], s[84:85] op_sel_hi:[1,0]
	v_lshlrev_b32_e32 v192, 16, v171
	v_and_b32_e32 v171, 0xffff0000, v171
	v_cndmask_b32_e64 v87, v157, v103, s[6:7]
	v_cndmask_b32_e64 v86, v156, v102, s[6:7]
	v_pk_mul_f32 v[80:81], v[80:81], s[84:85] op_sel_hi:[1,0]
	v_pk_fma_f32 v[76:77], v[76:77], v[84:85], v[82:83]
	v_lshlrev_b32_e32 v190, 16, v170
	v_and_b32_e32 v170, 0xffff0000, v170
	v_pk_fma_f32 v[78:79], v[78:79], v[86:87], v[80:81]
	v_cvt_pk_bf16_f32 v195, v76, v77
	v_sub_f32_e32 v77, v171, v146
	v_sub_f32_e32 v76, v192, v146
	v_cvt_pk_bf16_f32 v191, v78, v79
	v_sub_f32_e32 v79, v170, v146
	v_sub_f32_e32 v78, v190, v146
	v_pk_mul_f32 v[76:77], v[146:147], v[76:77] op_sel:[1,0]
	v_pk_mul_f32 v[78:79], v[146:147], v[78:79] op_sel:[1,0]
	v_pk_fma_f32 v[76:77], v[94:95], v[76:77], v[98:99]
	v_pk_fma_f32 v[78:79], v[92:93], v[78:79], v[96:97]
	v_cndmask_b32_e64 v83, v157, v103, s[8:9]
	v_cndmask_b32_e64 v82, v156, v102, s[8:9]
	v_pk_mul_f32 v[76:77], v[76:77], s[84:85] op_sel_hi:[1,0]
	v_lshlrev_b32_e32 v194, 16, v176
	v_and_b32_e32 v176, 0xffff0000, v176
	v_cndmask_b32_e64 v81, v155, v101, s[8:9]
	v_cndmask_b32_e64 v80, v154, v100, s[8:9]
	v_pk_mul_f32 v[78:79], v[78:79], s[84:85] op_sel_hi:[1,0]
	v_pk_fma_f32 v[30:31], v[30:31], v[82:83], v[76:77]
	v_pk_fma_f32 v[28:29], v[28:29], v[80:81], v[78:79]
	v_lshlrev_b32_e32 v196, 16, v177
	v_cvt_pk_bf16_f32 v205, v28, v29
	v_cvt_pk_bf16_f32 v201, v30, v31
	v_sub_f32_e32 v31, v176, v0
	v_sub_f32_e32 v30, v194, v0
	v_and_b32_e32 v177, 0xffff0000, v177
	v_pk_mul_f32 v[30:31], v[0:1], v[30:31] op_sel:[1,0]
	v_sub_f32_e32 v29, v177, v0
	v_sub_f32_e32 v28, v196, v0
	v_pk_fma_f32 v[30:31], v[92:93], v[30:31], v[96:97]
	v_pk_mul_f32 v[28:29], v[0:1], v[28:29] op_sel:[1,0]
	v_cndmask_b32_e64 v77, v155, v101, s[10:11]
	v_cndmask_b32_e64 v76, v154, v100, s[10:11]
	v_pk_mul_f32 v[30:31], v[30:31], s[84:85] op_sel_hi:[1,0]
	v_pk_fma_f32 v[28:29], v[94:95], v[28:29], v[98:99]
	v_pk_fma_f32 v[24:25], v[24:25], v[76:77], v[30:31]
	v_cndmask_b32_e64 v79, v157, v103, s[10:11]
	v_cndmask_b32_e64 v78, v156, v102, s[10:11]
	v_pk_mul_f32 v[28:29], v[28:29], s[84:85] op_sel_hi:[1,0]
	v_cvt_pk_bf16_f32 v215, v24, v25
	v_add_u32_e32 v24, 0x80, v134
	v_pk_fma_f32 v[26:27], v[26:27], v[78:79], v[28:29]
	v_readlane_b32 s44, v255, 23
	v_cvt_pk_bf16_f32 v164, v26, v27
	v_readlane_b32 s45, v255, 24
	v_ashrrev_i32_e32 v25, 31, v24
	v_lshl_add_u64 v[26:27], v[24:25], 1, s[58:59]
	v_lshl_add_u64 v[28:29], v[26:27], 0, v[142:143]
	v_lshl_add_u64 v[30:31], v[26:27], 0, v[140:141]
	v_lshl_add_u64 v[76:77], v[26:27], 0, v[138:139]
	v_lshl_add_u64 v[78:79], v[26:27], 0, v[136:137]
	global_load_dwordx2 v[96:97], v[28:29], off
	global_load_dwordx2 v[98:99], v[30:31], off
	global_load_dwordx2 v[100:101], v[76:77], off
	global_load_dwordx2 v[102:103], v[78:79], off
	v_lshl_add_u64 v[28:29], v[26:27], 0, v[132:133]
	v_lshl_add_u64 v[26:27], v[26:27], 0, v[130:131]
	global_load_dwordx2 v[144:145], v[28:29], off
	global_load_dwordx2 v[154:155], v[26:27], off
	v_lshlrev_b64 v[28:29], 2, v[24:25]
	v_lshl_add_u64 v[30:31], s[46:47], 0, v[28:29]
	global_load_dwordx4 v[76:79], v[30:31], off
	v_lshl_add_u64 v[30:31], s[48:49], 0, v[28:29]
	v_lshl_add_u64 v[24:25], s[0:1], 0, v[28:29]
	v_lshl_add_u64 v[26:27], s[76:77], 0, v[28:29]
	global_load_dwordx4 v[80:83], v[30:31], off
	global_load_dwordx4 v[84:87], v[24:25], off
	global_load_dwordx4 v[92:95], v[26:27], off
	v_lshl_add_u64 v[24:25], s[16:17], 0, v[28:29]
	v_lshl_add_u64 v[28:29], s[18:19], 0, v[28:29]
	global_load_dwordx4 v[24:27], v[24:25], off
	v_readlane_b32 s50, v255, 29
	global_load_dwordx4 v[28:31], v[28:29], off
	s_waitcnt vmcnt(6)
	s_nop 0
	v_lshlrev_b32_e32 v89, 16, v96
	v_and_b32_e32 v90, 0xffff0000, v96
	v_lshlrev_b32_e32 v96, 16, v97
	v_and_b32_e32 v97, 0xffff0000, v97
	v_sub_f32_e32 v97, v97, v158
	v_sub_f32_e32 v96, v96, v158
	v_lshlrev_b32_e32 v104, 16, v98
	v_and_b32_e32 v106, 0xffff0000, v98
	v_lshlrev_b32_e32 v117, 16, v99
	v_and_b32_e32 v156, 0xffff0000, v99
	v_sub_f32_e32 v99, v90, v158
	v_sub_f32_e32 v98, v89, v158
	v_pk_mul_f32 v[96:97], v[158:159], v[96:97] op_sel:[1,0]
	v_pk_mul_f32 v[98:99], v[158:159], v[98:99] op_sel:[1,0]
	s_waitcnt vmcnt(4)
	v_pk_fma_f32 v[96:97], v[78:79], v[96:97], v[82:83]
	v_lshlrev_b32_e32 v168, 16, v102
	v_and_b32_e32 v169, 0xffff0000, v102
	v_lshlrev_b32_e32 v170, 16, v103
	v_and_b32_e32 v171, 0xffff0000, v103
	v_pk_fma_f32 v[98:99], v[76:77], v[98:99], v[80:81]
	s_waitcnt vmcnt(2)
	v_cndmask_b32_e64 v103, v95, v87, s[12:13]
	v_cndmask_b32_e64 v102, v94, v86, s[12:13]
	v_pk_mul_f32 v[96:97], v[96:97], s[84:85] op_sel_hi:[1,0]
	v_lshlrev_b32_e32 v157, 16, v100
	v_and_b32_e32 v160, 0xffff0000, v100
	v_lshlrev_b32_e32 v161, 16, v101
	v_and_b32_e32 v166, 0xffff0000, v101
	v_cndmask_b32_e64 v101, v93, v85, s[12:13]
	v_cndmask_b32_e64 v100, v92, v84, s[12:13]
	v_pk_mul_f32 v[98:99], v[98:99], s[84:85] op_sel_hi:[1,0]
	v_pk_fma_f32 v[74:75], v[74:75], v[102:103], v[96:97]
	v_pk_fma_f32 v[72:73], v[72:73], v[100:101], v[98:99]
	v_cndmask_b32_e32 v97, v93, v85, vcc
	v_cvt_pk_bf16_f32 v90, v72, v73
	v_cvt_pk_bf16_f32 v182, v74, v75
	v_sub_f32_e32 v75, v106, v152
	v_sub_f32_e32 v74, v104, v152
	v_sub_f32_e32 v73, v156, v152
	v_sub_f32_e32 v72, v117, v152
	v_pk_mul_f32 v[74:75], v[152:153], v[74:75] op_sel:[1,0]
	v_pk_mul_f32 v[72:73], v[152:153], v[72:73] op_sel:[1,0]
	v_pk_fma_f32 v[74:75], v[76:77], v[74:75], v[80:81]
	v_pk_fma_f32 v[72:73], v[78:79], v[72:73], v[82:83]
	v_cndmask_b32_e32 v96, v92, v84, vcc
	v_pk_mul_f32 v[74:75], v[74:75], s[84:85] op_sel_hi:[1,0]
	v_cndmask_b32_e32 v99, v95, v87, vcc
	v_cndmask_b32_e32 v98, v94, v86, vcc
	v_pk_mul_f32 v[72:73], v[72:73], s[84:85] op_sel_hi:[1,0]
	v_pk_fma_f32 v[68:69], v[68:69], v[96:97], v[74:75]
	v_pk_fma_f32 v[70:71], v[70:71], v[98:99], v[72:73]
	v_cvt_pk_bf16_f32 v177, v68, v69
	v_sub_f32_e32 v69, v166, v150
	v_sub_f32_e32 v68, v161, v150
	v_cvt_pk_bf16_f32 v176, v70, v71
	v_sub_f32_e32 v71, v160, v150
	v_sub_f32_e32 v70, v157, v150
	v_pk_mul_f32 v[68:69], v[150:151], v[68:69] op_sel:[1,0]
	v_pk_mul_f32 v[70:71], v[150:151], v[70:71] op_sel:[1,0]
	v_pk_fma_f32 v[68:69], v[78:79], v[68:69], v[82:83]
	v_pk_fma_f32 v[70:71], v[76:77], v[70:71], v[80:81]
	v_cndmask_b32_e64 v75, v95, v87, s[4:5]
	v_cndmask_b32_e64 v74, v94, v86, s[4:5]
	v_pk_mul_f32 v[68:69], v[68:69], s[84:85] op_sel_hi:[1,0]
	v_cndmask_b32_e64 v73, v93, v85, s[4:5]
	v_cndmask_b32_e64 v72, v92, v84, s[4:5]
	v_pk_mul_f32 v[70:71], v[70:71], s[84:85] op_sel_hi:[1,0]
	v_pk_fma_f32 v[66:67], v[66:67], v[74:75], v[68:69]
	v_pk_fma_f32 v[64:65], v[64:65], v[72:73], v[70:71]
	v_cndmask_b32_e64 v69, v93, v85, s[6:7]
	v_cvt_pk_bf16_f32 v187, v64, v65
	v_cvt_pk_bf16_f32 v186, v66, v67
	v_sub_f32_e32 v67, v169, v148
	v_sub_f32_e32 v66, v168, v148
	v_sub_f32_e32 v65, v171, v148
	v_sub_f32_e32 v64, v170, v148
	v_pk_mul_f32 v[66:67], v[148:149], v[66:67] op_sel:[1,0]
	v_pk_mul_f32 v[64:65], v[148:149], v[64:65] op_sel:[1,0]
	v_pk_fma_f32 v[66:67], v[76:77], v[66:67], v[80:81]
	v_pk_fma_f32 v[64:65], v[78:79], v[64:65], v[82:83]
	v_cndmask_b32_e64 v68, v92, v84, s[6:7]
	v_pk_mul_f32 v[66:67], v[66:67], s[84:85] op_sel_hi:[1,0]
	v_lshlrev_b32_e32 v174, 16, v145
	v_and_b32_e32 v145, 0xffff0000, v145
	v_cndmask_b32_e64 v71, v95, v87, s[6:7]
	v_cndmask_b32_e64 v70, v94, v86, s[6:7]
	v_pk_mul_f32 v[64:65], v[64:65], s[84:85] op_sel_hi:[1,0]
	v_pk_fma_f32 v[60:61], v[60:61], v[68:69], v[66:67]
	v_lshlrev_b32_e32 v172, 16, v144
	v_and_b32_e32 v144, 0xffff0000, v144
	v_pk_fma_f32 v[62:63], v[62:63], v[70:71], v[64:65]
	v_cvt_pk_bf16_f32 v197, v60, v61
	v_sub_f32_e32 v61, v145, v146
	v_sub_f32_e32 v60, v174, v146
	v_cvt_pk_bf16_f32 v196, v62, v63
	v_sub_f32_e32 v63, v144, v146
	v_sub_f32_e32 v62, v172, v146
	v_pk_mul_f32 v[60:61], v[146:147], v[60:61] op_sel:[1,0]
	v_pk_mul_f32 v[62:63], v[146:147], v[62:63] op_sel:[1,0]
	v_pk_fma_f32 v[60:61], v[78:79], v[60:61], v[82:83]
	v_pk_fma_f32 v[62:63], v[76:77], v[62:63], v[80:81]
	v_cndmask_b32_e64 v67, v95, v87, s[8:9]
	v_cndmask_b32_e64 v66, v94, v86, s[8:9]
	v_pk_mul_f32 v[60:61], v[60:61], s[84:85] op_sel_hi:[1,0]
	v_lshlrev_b32_e32 v179, 16, v154
	v_and_b32_e32 v154, 0xffff0000, v154
	v_cndmask_b32_e64 v65, v93, v85, s[8:9]
	v_cndmask_b32_e64 v64, v92, v84, s[8:9]
	v_pk_mul_f32 v[62:63], v[62:63], s[84:85] op_sel_hi:[1,0]
	v_pk_fma_f32 v[58:59], v[58:59], v[66:67], v[60:61]
	v_pk_fma_f32 v[56:57], v[56:57], v[64:65], v[62:63]
	v_lshlrev_b32_e32 v180, 16, v155
	v_cvt_pk_bf16_f32 v206, v56, v57
	v_cvt_pk_bf16_f32 v203, v58, v59
	v_sub_f32_e32 v59, v154, v0
	v_sub_f32_e32 v58, v179, v0
	v_and_b32_e32 v155, 0xffff0000, v155
	v_pk_mul_f32 v[58:59], v[0:1], v[58:59] op_sel:[1,0]
	v_sub_f32_e32 v57, v155, v0
	v_sub_f32_e32 v56, v180, v0
	v_pk_fma_f32 v[58:59], v[76:77], v[58:59], v[80:81]
	v_pk_mul_f32 v[56:57], v[0:1], v[56:57] op_sel:[1,0]
	v_cndmask_b32_e64 v61, v93, v85, s[10:11]
	v_cndmask_b32_e64 v60, v92, v84, s[10:11]
	v_pk_mul_f32 v[58:59], v[58:59], s[84:85] op_sel_hi:[1,0]
	v_pk_fma_f32 v[56:57], v[78:79], v[56:57], v[82:83]
	v_pk_fma_f32 v[52:53], v[52:53], v[60:61], v[58:59]
	v_cndmask_b32_e64 v63, v95, v87, s[10:11]
	v_cndmask_b32_e64 v62, v94, v86, s[10:11]
	v_pk_mul_f32 v[56:57], v[56:57], s[84:85] op_sel_hi:[1,0]
	v_cvt_pk_bf16_f32 v216, v52, v53
	v_add_u32_e32 v52, 0x84, v134
	v_pk_fma_f32 v[54:55], v[54:55], v[62:63], v[56:57]
	v_lshlrev_b32_e32 v144, 16, v88
	v_cvt_pk_bf16_f32 v213, v54, v55
	v_and_b32_e32 v145, 0xffff0000, v88
	v_ashrrev_i32_e32 v53, 31, v52
	v_lshl_add_u64 v[54:55], v[52:53], 1, s[58:59]
	v_lshl_add_u64 v[56:57], v[54:55], 0, v[142:143]
	v_lshl_add_u64 v[58:59], v[54:55], 0, v[140:141]
	v_lshl_add_u64 v[60:61], v[54:55], 0, v[138:139]
	v_lshl_add_u64 v[62:63], v[54:55], 0, v[136:137]
	global_load_dwordx2 v[80:81], v[56:57], off
	global_load_dwordx2 v[82:83], v[58:59], off
	global_load_dwordx2 v[100:101], v[60:61], off
	global_load_dwordx2 v[102:103], v[62:63], off
	v_lshl_add_u64 v[56:57], v[54:55], 0, v[132:133]
	v_lshl_add_u64 v[54:55], v[54:55], 0, v[130:131]
	global_load_dwordx2 v[160:161], v[56:57], off
	global_load_dwordx2 v[168:169], v[54:55], off
	v_lshlrev_b64 v[56:57], 2, v[52:53]
	v_lshl_add_u64 v[58:59], s[46:47], 0, v[56:57]
	global_load_dwordx4 v[64:67], v[58:59], off
	v_lshl_add_u64 v[58:59], s[48:49], 0, v[56:57]
	v_lshl_add_u64 v[52:53], s[0:1], 0, v[56:57]
	v_lshl_add_u64 v[54:55], s[76:77], 0, v[56:57]
	global_load_dwordx4 v[72:75], v[58:59], off
	global_load_dwordx4 v[60:63], v[52:53], off
	global_load_dwordx4 v[68:71], v[54:55], off
	v_lshl_add_u64 v[52:53], s[16:17], 0, v[56:57]
	v_lshlrev_b32_e32 v58, 2, v2
	global_load_dwordx4 v[52:55], v[52:53], off
	v_lshl_add_u64 v[56:57], s[18:19], 0, v[56:57]
	v_xor_b32_e32 v227, 64, v58
	v_xor_b32_e32 v226, 0x80, v58
	global_load_dwordx4 v[56:59], v[56:57], off
	v_mul_f32_e32 v76, v144, v144
	v_pk_fma_f32 v[88:89], v[144:145], v[144:145], v[76:77] op_sel_hi:[1,1,0]
	v_lshlrev_b32_e32 v76, 16, v90
	v_and_b32_e32 v77, 0xffff0000, v90
	v_lshlrev_b32_e32 v78, 16, v182
	v_and_b32_e32 v79, 0xffff0000, v182
	s_waitcnt vmcnt(13)
	v_pk_mul_f32 v[92:93], v[24:25], v[76:77]
	v_pk_mul_f32 v[170:171], v[26:27], v[78:79]
	s_waitcnt vmcnt(12)
	v_pk_mul_f32 v[208:209], v[28:29], v[92:93]
	v_pk_mul_f32 v[198:199], v[30:31], v[170:171]
	v_pk_mul_f32 v[86:87], v[24:25], v[92:93]
	v_add_f32_e32 v88, v92, v93
	v_mul_f32_e32 v94, v93, v93
	v_add_f32_e32 v93, v208, v209
	v_add_f32_e32 v104, v198, v199
	v_add_f32_e32 v93, v93, v104
	s_waitcnt vmcnt(6)
	s_nop 0
	v_lshlrev_b32_e32 v104, 16, v80
	v_and_b32_e32 v106, 0xffff0000, v80
	v_lshlrev_b32_e32 v80, 16, v81
	v_and_b32_e32 v81, 0xffff0000, v81
	v_lshlrev_b32_e32 v117, 16, v82
	v_and_b32_e32 v155, 0xffff0000, v82
	v_lshlrev_b32_e32 v157, 16, v83
	v_and_b32_e32 v166, 0xffff0000, v83
	v_sub_f32_e32 v83, v106, v158
	v_sub_f32_e32 v82, v104, v158
	v_sub_f32_e32 v81, v81, v158
	v_sub_f32_e32 v80, v80, v158
	v_pk_mul_f32 v[82:83], v[158:159], v[82:83] op_sel:[1,0]
	v_pk_mul_f32 v[80:81], v[158:159], v[80:81] op_sel:[1,0]
	s_waitcnt vmcnt(4)
	v_pk_fma_f32 v[82:83], v[64:65], v[82:83], v[72:73]
	v_lshlrev_b32_e32 v172, 16, v100
	v_and_b32_e32 v174, 0xffff0000, v100
	v_lshlrev_b32_e32 v179, 16, v101
	v_and_b32_e32 v180, 0xffff0000, v101
	v_pk_fma_f32 v[80:81], v[66:67], v[80:81], v[74:75]
	s_waitcnt vmcnt(2)
	v_cndmask_b32_e64 v101, v69, v61, s[12:13]
	v_cndmask_b32_e64 v100, v68, v60, s[12:13]
	v_pk_mul_f32 v[82:83], v[82:83], s[84:85] op_sel_hi:[1,0]
	v_lshlrev_b32_e32 v182, 16, v102
	v_and_b32_e32 v184, 0xffff0000, v102
	v_lshlrev_b32_e32 v189, 16, v103
	v_and_b32_e32 v190, 0xffff0000, v103
	v_cndmask_b32_e64 v103, v71, v63, s[12:13]
	v_cndmask_b32_e64 v102, v70, v62, s[12:13]
	v_pk_mul_f32 v[80:81], v[80:81], s[84:85] op_sel_hi:[1,0]
	v_pk_fma_f32 v[48:49], v[48:49], v[100:101], v[82:83]
	v_pk_fma_f32 v[50:51], v[50:51], v[102:103], v[80:81]
	v_cvt_pk_bf16_f32 v48, v48, v49
	v_add_f32_e32 v90, v170, v171
	v_cvt_pk_bf16_f32 v49, v50, v51
	v_lshlrev_b32_e32 v80, 16, v48
	v_and_b32_e32 v81, 0xffff0000, v48
	v_lshlrev_b32_e32 v82, 16, v49
	v_and_b32_e32 v83, 0xffff0000, v49
	s_waitcnt vmcnt(1)
	v_pk_mul_f32 v[100:101], v[52:53], v[80:81]
	v_pk_mul_f32 v[102:103], v[54:55], v[82:83]
	v_pk_mul_f32 v[84:85], v[26:27], v[170:171]
	v_add_f32_e32 v95, v88, v90
	v_mul_f32_e32 v88, v170, v170
	v_mul_f32_e32 v90, v171, v171
	v_lshlrev_b32_e32 v204, 16, v168
	v_and_b32_e32 v207, 0xffff0000, v168
	v_lshlrev_b32_e32 v208, 16, v169
	v_and_b32_e32 v209, 0xffff0000, v169
	s_waitcnt vmcnt(0)
	v_pk_mul_f32 v[168:169], v[58:59], v[102:103]
	v_pk_mul_f32 v[170:171], v[56:57], v[100:101]
	v_add_f32_e32 v104, v100, v101
	v_add_f32_e32 v106, v102, v103
	v_pk_mul_f32 v[48:49], v[54:55], v[102:103]
	v_pk_mul_f32 v[50:51], v[52:53], v[100:101]
	v_add_f32_e32 v210, v104, v106
	v_mul_f32_e32 v104, v100, v100
	v_mul_f32_e32 v106, v101, v101
	v_mul_f32_e32 v100, v102, v102
	v_mul_f32_e32 v102, v103, v103
	v_add_f32_e32 v101, v170, v171
	v_add_f32_e32 v103, v168, v169
	v_sub_f32_e32 v169, v166, v152
	v_sub_f32_e32 v168, v157, v152
	v_sub_f32_e32 v171, v155, v152
	v_sub_f32_e32 v170, v117, v152
	v_pk_mul_f32 v[170:171], v[152:153], v[170:171] op_sel:[1,0]
	v_pk_mul_f32 v[152:153], v[152:153], v[168:169] op_sel:[1,0]
	v_pk_fma_f32 v[168:169], v[64:65], v[170:171], v[72:73]
	v_pk_fma_f32 v[152:153], v[66:67], v[152:153], v[74:75]
	v_cndmask_b32_e32 v171, v69, v61, vcc
	v_cndmask_b32_e32 v170, v68, v60, vcc
	v_cndmask_b32_e32 v199, v71, v63, vcc
	v_cndmask_b32_e32 v198, v70, v62, vcc
	v_pk_mul_f32 v[168:169], v[168:169], s[84:85] op_sel_hi:[1,0]
	v_pk_mul_f32 v[152:153], v[152:153], s[84:85] op_sel_hi:[1,0]
	v_pk_fma_f32 v[44:45], v[44:45], v[170:171], v[168:169]
	v_pk_fma_f32 v[46:47], v[46:47], v[198:199], v[152:153]
	v_cvt_pk_bf16_f32 v45, v44, v45
	v_sub_f32_e32 v153, v174, v150
	v_cvt_pk_bf16_f32 v44, v46, v47
	v_sub_f32_e32 v47, v180, v150
	v_sub_f32_e32 v46, v179, v150
	v_sub_f32_e32 v152, v172, v150
	v_pk_mul_f32 v[152:153], v[150:151], v[152:153] op_sel:[1,0]
	v_pk_mul_f32 v[46:47], v[150:151], v[46:47] op_sel:[1,0]
	v_pk_fma_f32 v[150:151], v[64:65], v[152:153], v[72:73]
	v_pk_fma_f32 v[46:47], v[66:67], v[46:47], v[74:75]
	v_cndmask_b32_e64 v153, v69, v61, s[4:5]
	v_cndmask_b32_e64 v152, v68, v60, s[4:5]
	v_cndmask_b32_e64 v169, v71, v63, s[4:5]
	v_cndmask_b32_e64 v168, v70, v62, s[4:5]
	v_pk_mul_f32 v[150:151], v[150:151], s[84:85] op_sel_hi:[1,0]
	v_pk_mul_f32 v[46:47], v[46:47], s[84:85] op_sel_hi:[1,0]
	v_pk_fma_f32 v[40:41], v[40:41], v[152:153], v[150:151]
	v_pk_fma_f32 v[46:47], v[42:43], v[168:169], v[46:47]
	v_cvt_pk_bf16_f32 v43, v40, v41
	v_sub_f32_e32 v41, v190, v148
	v_cvt_pk_bf16_f32 v42, v46, v47
	v_sub_f32_e32 v40, v189, v148
	v_sub_f32_e32 v47, v184, v148
	v_sub_f32_e32 v46, v182, v148
	v_pk_mul_f32 v[46:47], v[148:149], v[46:47] op_sel:[1,0]
	v_pk_mul_f32 v[40:41], v[148:149], v[40:41] op_sel:[1,0]
	v_pk_fma_f32 v[46:47], v[64:65], v[46:47], v[72:73]
	v_pk_fma_f32 v[40:41], v[66:67], v[40:41], v[74:75]
	v_cndmask_b32_e64 v149, v69, v61, s[6:7]
	v_cndmask_b32_e64 v148, v68, v60, s[6:7]
	v_cndmask_b32_e64 v151, v71, v63, s[6:7]
	v_cndmask_b32_e64 v150, v70, v62, s[6:7]
	v_pk_mul_f32 v[46:47], v[46:47], s[84:85] op_sel_hi:[1,0]
	v_pk_mul_f32 v[40:41], v[40:41], s[84:85] op_sel_hi:[1,0]
	v_lshlrev_b32_e32 v192, 16, v160
	v_and_b32_e32 v194, 0xffff0000, v160
	v_lshlrev_b32_e32 v200, 16, v161
	v_and_b32_e32 v202, 0xffff0000, v161
	v_pk_fma_f32 v[38:39], v[38:39], v[150:151], v[40:41]
	v_pk_fma_f32 v[36:37], v[36:37], v[148:149], v[46:47]
	v_cndmask_b32_e64 v47, v69, v61, s[8:9]
	v_cvt_pk_bf16_f32 v41, v36, v37
	v_cvt_pk_bf16_f32 v40, v38, v39
	v_sub_f32_e32 v37, v202, v146
	v_sub_f32_e32 v36, v200, v146
	v_sub_f32_e32 v39, v194, v146
	v_sub_f32_e32 v38, v192, v146
	v_pk_mul_f32 v[38:39], v[146:147], v[38:39] op_sel:[1,0]
	v_pk_mul_f32 v[36:37], v[146:147], v[36:37] op_sel:[1,0]
	v_pk_fma_f32 v[38:39], v[64:65], v[38:39], v[72:73]
	v_pk_fma_f32 v[36:37], v[66:67], v[36:37], v[74:75]
	v_cndmask_b32_e64 v46, v68, v60, s[8:9]
	v_cndmask_b32_e64 v147, v71, v63, s[8:9]
	v_cndmask_b32_e64 v146, v70, v62, s[8:9]
	v_pk_mul_f32 v[38:39], v[38:39], s[84:85] op_sel_hi:[1,0]
	v_pk_mul_f32 v[36:37], v[36:37], s[84:85] op_sel_hi:[1,0]
	v_pk_fma_f32 v[32:33], v[32:33], v[46:47], v[38:39]
	v_pk_fma_f32 v[34:35], v[34:35], v[146:147], v[36:37]
	v_cvt_pk_bf16_f32 v39, v32, v33
	v_sub_f32_e32 v33, v209, v0
	v_cvt_pk_bf16_f32 v38, v34, v35
	v_sub_f32_e32 v32, v208, v0
	v_sub_f32_e32 v35, v207, v0
	v_sub_f32_e32 v34, v204, v0
	v_pk_mul_f32 v[34:35], v[0:1], v[34:35] op_sel:[1,0]
	v_pk_mul_f32 v[0:1], v[0:1], v[32:33] op_sel:[1,0]
	v_and_b32_e32 v154, 0xffff0000, v107
	v_pk_fma_f32 v[0:1], v[66:67], v[0:1], v[74:75]
	v_lshlrev_b32_e32 v156, 16, v105
	v_pk_fma_f32 v[32:33], v[64:65], v[34:35], v[72:73]
	v_cndmask_b32_e64 v35, v71, v63, s[10:11]
	v_cndmask_b32_e64 v34, v70, v62, s[10:11]
	v_pk_mul_f32 v[0:1], v[0:1], s[84:85] op_sel_hi:[1,0]
	v_lshlrev_b32_e32 v168, 16, v107
	v_and_b32_e32 v171, 0xffff0000, v91
	v_and_b32_e32 v170, 0xffff0000, v105
	v_pk_fma_f32 v[62:63], v[22:23], v[34:35], v[0:1]
	v_lshlrev_b32_e32 v169, 16, v91
	v_mov_b32_e32 v157, v171
	v_mov_b32_e32 v0, v156
	v_mov_b32_e32 v1, v170
	v_mov_b32_e32 v22, v168
	v_mov_b32_e32 v23, v154
	v_mov_b32_e32 v155, v169
	v_pk_mul_f32 v[0:1], v[6:7], v[0:1]
	v_pk_mul_f32 v[22:23], v[4:5], v[22:23]
	v_pk_mul_f32 v[70:71], v[156:157], v[156:157]
	v_cndmask_b32_e64 v37, v69, v61, s[10:11]
	v_cndmask_b32_e64 v36, v68, v60, s[10:11]
	v_pk_mul_f32 v[66:67], v[168:169], v[168:169]
	v_pk_mul_f32 v[68:69], v[154:155], v[154:155]
	v_add_f32_e32 v71, v22, v23
	v_add_f32_e32 v74, v0, v1
	v_pk_mul_f32 v[72:73], v[170:171], v[170:171]
	v_add_f32_e32 v71, v71, v74
	v_pk_mov_b32 v[150:151], v[168:169], v[66:67] op_sel:[1,0]
	v_pk_mov_b32 v[68:69], v[170:171], v[68:69] op_sel:[1,0]
	v_add_f32_e32 v91, 0, v71
	v_pk_add_f32 v[68:69], v[150:151], v[68:69]
	v_mov_b32_e32 v150, v144
	v_mov_b32_e32 v151, v70
	v_pk_mov_b32 v[70:71], v[144:145], v[72:73] op_sel:[1,0]
	v_pk_mul_f32 v[34:35], v[4:5], v[22:23]
	v_pk_add_f32 v[70:71], v[150:151], v[70:71]
	v_pk_mul_f32 v[46:47], v[10:11], v[0:1]
	v_pk_mul_f32 v[64:65], v[8:9], v[22:23]
	v_mul_f32_e32 v74, v22, v22
	v_mul_f32_e32 v22, v1, v1
	v_pk_add_f32 v[68:69], v[68:69], v[70:71]
	v_pk_add_f32 v[70:71], v[168:169], v[154:155]
	v_pk_mul_f32 v[60:61], v[32:33], s[84:85] op_sel_hi:[1,0]
	v_pk_mul_f32 v[32:33], v[6:7], v[0:1]
	v_pk_fma_f32 v[148:149], v[0:1], v[0:1], v[22:23] op_sel_hi:[1,1,0]
	v_add_f32_e32 v0, v64, v65
	v_add_f32_e32 v1, v46, v47
	v_mov_b32_e32 v71, v67
	v_pk_add_f32 v[66:67], v[170:171], v[156:157]
	v_add_f32_e32 v0, v0, v1
	v_mov_b32_e32 v67, v73
	v_add_f32_e32 v101, v101, v103
	v_add_f32_e32 v103, 0, v0
	v_mov_b32_e32 v0, v169
	v_mov_b32_e32 v1, v171
	v_pk_add_f32 v[66:67], v[70:71], v[66:67]
	v_mov_b32_e32 v117, v89
	v_mul_f32_e32 v146, v23, v23
	v_pk_mul_f32 v[0:1], v[12:13], v[0:1]
	v_pk_mul_f32 v[22:23], v[14:15], v[144:145]
	v_pk_add_f32 v[66:67], v[66:67], v[116:117]
	v_pk_mul_f32 v[46:47], v[16:17], v[0:1]
	v_pk_add_f32 v[66:67], v[68:69], v[66:67]
	v_add_f32_e32 v68, v0, v1
	v_add_f32_e32 v69, v22, v23
	v_pk_mul_f32 v[64:65], v[18:19], v[22:23]
	v_add_f32_e32 v68, v68, v69
	v_add_f32_e32 v147, v32, v33
	v_pk_mul_f32 v[32:33], v[12:13], v[0:1]
	v_add_f32_e32 v69, v91, v68
	v_mul_f32_e32 v68, v0, v0
	v_mul_f32_e32 v70, v1, v1
	v_add_f32_e32 v0, v46, v47
	v_add_f32_e32 v1, v64, v65
	v_pk_mul_f32 v[98:99], v[76:77], v[76:77]
	v_pk_mul_f32 v[96:97], v[78:79], v[78:79]
	v_add_f32_e32 v0, v0, v1
	v_add_f32_e32 v75, v34, v35
	v_pk_mul_f32 v[34:35], v[14:15], v[22:23]
	v_mul_f32_e32 v72, v22, v22
	v_mul_f32_e32 v150, v23, v23
	v_add_f32_e32 v64, v103, v0
	v_mov_b32_e32 v0, v76
	v_mov_b32_e32 v1, v98
	v_mov_b32_e32 v98, v77
	v_mov_b32_e32 v22, v78
	v_mov_b32_e32 v23, v96
	v_mov_b32_e32 v96, v79
	v_pk_mul_f32 v[160:161], v[80:81], v[80:81]
	v_pk_mul_f32 v[158:159], v[82:83], v[82:83]
	v_pk_add_f32 v[0:1], v[0:1], v[98:99]
	v_pk_add_f32 v[22:23], v[22:23], v[96:97]
	v_mov_b32_e32 v46, v82
	v_pk_add_f32 v[0:1], v[0:1], v[22:23]
	v_mov_b32_e32 v22, v80
	v_mov_b32_e32 v23, v160
	v_mov_b32_e32 v160, v81
	v_mov_b32_e32 v47, v158
	v_mov_b32_e32 v158, v83
	v_pk_add_f32 v[22:23], v[22:23], v[160:161]
	v_pk_add_f32 v[46:47], v[46:47], v[158:159]
	v_pk_add_f32 v[0:1], v[66:67], v[0:1]
	v_pk_add_f32 v[22:23], v[22:23], v[46:47]
	v_add_f32_e32 v47, v64, v93
	v_add_f32_e32 v67, v47, v101
	v_mov_b32_e32 v105, v50
	v_mov_b32_e32 v107, v51
	v_mov_b32_e32 v101, v48
	v_mov_b32_e32 v103, v49
	v_add_f32_e32 v46, v69, v95
	v_pk_add_f32 v[50:51], v[104:105], v[106:107]
	v_pk_add_f32 v[48:49], v[100:101], v[102:103]
	v_mov_b32_e32 v69, v32
	v_mov_b32_e32 v71, v33
	v_mov_b32_e32 v73, v34
	v_mov_b32_e32 v151, v35
	v_mul_f32_e32 v92, v92, v92
	v_mov_b32_e32 v93, v86
	v_mov_b32_e32 v95, v87
	v_mov_b32_e32 v89, v84
	v_mov_b32_e32 v91, v85
	v_pk_add_f32 v[48:49], v[50:51], v[48:49]
	v_pk_add_f32 v[50:51], v[74:75], v[146:147]
	v_mov_b32_e32 v149, v116
	v_pk_add_f32 v[32:33], v[68:69], v[70:71]
	v_pk_add_f32 v[34:35], v[72:73], v[150:151]
	v_add_f32_e32 v66, v46, v210
	v_pk_add_f32 v[46:47], v[92:93], v[94:95]
	v_pk_add_f32 v[64:65], v[88:89], v[90:91]
	v_pk_add_f32 v[50:51], v[50:51], v[148:149]
	v_pk_add_f32 v[32:33], v[32:33], v[34:35]
	v_pk_add_f32 v[46:47], v[46:47], v[64:65]
	v_pk_add_f32 v[32:33], v[50:51], v[32:33]
	v_pk_add_f32 v[0:1], v[0:1], v[22:23]
	v_pk_add_f32 v[32:33], v[32:33], v[46:47]
	ds_bpermute_b32 v22, v227, v0
	v_pk_add_f32 v[32:33], v[32:33], v[48:49]
	ds_bpermute_b32 v23, v227, v1
	ds_bpermute_b32 v96, v227, v66
	ds_bpermute_b32 v34, v227, v32
	ds_bpermute_b32 v35, v227, v33
	ds_bpermute_b32 v48, v227, v67
	s_waitcnt lgkmcnt(4)
	v_pk_add_f32 v[0:1], v[0:1], v[22:23]
	s_waitcnt lgkmcnt(3)
	v_add_f32_e32 v46, v66, v96
	ds_bpermute_b32 v22, v226, v0
	s_waitcnt lgkmcnt(2)
	v_pk_add_f32 v[32:33], v[32:33], v[34:35]
	s_waitcnt lgkmcnt(1)
	v_add_f32_e32 v48, v67, v48
	ds_bpermute_b32 v23, v226, v1
	ds_bpermute_b32 v47, v226, v46
	ds_bpermute_b32 v34, v226, v32
	ds_bpermute_b32 v35, v226, v33
	ds_bpermute_b32 v49, v226, v48
	v_cmp_gt_u32_e32 vcc, 16, v2
	v_readlane_b32 s51, v255, 30
	v_readlane_b32 s52, v255, 31
	v_readlane_b32 s53, v255, 32
	v_readlane_b32 s54, v255, 33
	v_readlane_b32 s55, v255, 34
	v_readlane_b32 s20, v254, 7
	v_readlane_b32 s21, v254, 8
	v_readlane_b32 s22, v254, 9
	v_readlane_b32 s23, v254, 10
	v_readlane_b32 s24, v254, 11
	v_readlane_b32 s25, v254, 12
	v_readlane_b32 s26, v254, 13
	v_readlane_b32 s27, v254, 14
	v_readlane_b32 s28, v254, 15
	v_readlane_b32 s29, v254, 16
	v_readlane_b32 s30, v254, 17
	v_readlane_b32 s31, v254, 18
	v_pk_fma_f32 v[20:21], v[20:21], v[36:37], v[60:61]
	s_nop 0
	v_cvt_pk_bf16_f32 v37, v20, v21
	v_cvt_pk_bf16_f32 v36, v62, v63
	s_and_saveexec_b64 s[0:1], vcc
	s_cbranch_execz .LBB0_2989
	s_add_i32 s4, s97, 0
	s_waitcnt lgkmcnt(0)
	v_add_f32_e32 v50, v48, v49
	v_pk_add_f32 v[48:49], v[32:33], v[34:35]
	v_pk_add_f32 v[32:33], v[0:1], v[22:23]
	v_lshl_add_u32 v0, v127, 7, s4
	v_add_f32_e32 v34, v46, v47
	v_add_u32_e32 v0, 0x20000, v0
	v_mov_b32_e32 v35, v116
	v_mov_b32_e32 v51, v116
	ds_write_b128 v0, v[32:35]
	ds_write_b128 v0, v[48:51] offset:16
